# baseline (speedup 1.0000x reference)
; #define LAS __attribute__((address_space(3)))
; __device__ __forceinline__ float swap_max(float v) { unsigned a = __builtin_bit_cast(unsigned, v), b = a; asm volatile("s_nop 1\n\tv_permlane32_swap_b32 %0, %1\n\ts_nop 1" : "+v"(a), "+v"(b)); return fmaxf(__builtin_bit_cast(float, a), __builtin_bit_cast(float, b)); }
; #define LOAD_K(t) do { _Pragma("unroll") for (int i = 0; i < KCH; ++i) kreg[i] = *(const u32x4*)((const char*)kg + (size_t)((t) * 64 + i * RPPK) * (LD * 2) + kvoff); } while (0)
; template <int MODE>
; __device__ __forceinline__ void attn_unit(LAS unsigned char* lds, const bf16_t* __restrict__ qkvz, bf16_t* __restrict__ A2, const int b, const int hd, const int qb, const AttnX& X, const int tid) {
;     ...
;         if (PF2) { if (has_next) { STORE_K(nxt); if (PF2V) STORE_V(nxt); } if (n + 2 < NT) { LOAD_K(TILE(n + 2)); if (PF2V) LOAD_V(TILE(n + 2)); } }
;         else if (has_next) LOAD_K(TILE(n + 1));
;         if (WIDE) {
; #pragma unroll
;             for (int kk = 0; kk < 2; ++kk) {
;                 if (active) {
;                     f32x16 S;
; #pragma unroll
;                     for (int i = 0; i < 16; ++i) S[i] = 0.f;
;                     const LAS unsigned char* kb = lds + cur * STG + kbase_off + kk * 32 * PK;
;                     __builtin_amdgcn_s_setprio(1);
; #pragma unroll
;                     for (int s = 0; s < NS; ++s) { const bf16x8 a0 = *(const LAS bf16x8*)(kb + s * 32); S = __builtin_amdgcn_mfma_f32_32x32x16_bf16(a0, qf[s], S, 0, 0, 0); }
;                     __builtin_amdgcn_s_setprio(0);
;                     S = S * c2;
;                     float a0 = fmaxf(fmaxf(S[0], S[1]), S[2]), a1 = fmaxf(fmaxf(S[3], S[4]), S[5]);
; #pragma unroll
;                     for (int i = 6; i < 14; i += 4) { a0 = fmaxf(fmaxf(a0, S[i]), S[i + 1]); a1 = fmaxf(fmaxf(a1, S[i + 2]), S[i + 3]); }
;                     const float mx = swap_max(fmaxf(fmaxf(a0, a1), fmaxf(S[14], S[15])));
;                     const float m_new = fmaxf(m_run, mx);
;                     if (__any(mx > m_run + RESCALE_THR)) {
;                         const float alpha = __builtin_amdgcn_exp2f(m_run - m_new);
;                         l_run *= alpha;
; #pragma unroll
;                         for (int d = 0; d < NDT; ++d) O[d] = O[d] * alpha;
;                         m_run = m_new;
;                     }
.Ldf_nodelay:
	v_add_co_u32_e32 v2, vcc, s30, v222
	s_and_b32 s0, s41, 1
	s_nop 0
	v_addc_co_u32_e32 v3, vcc, -1, v223, vcc
	v_add_co_u32_e32 v6, vcc, 0xfff7f000, v222
	s_cmp_le_u32 s41, s39
	s_nop 0
	v_addc_co_u32_e32 v7, vcc, -1, v223, vcc
	v_add_co_u32_e32 v10, vcc, 0xfffbf000, v222
	global_load_dwordx4 v[2:5], v[2:3], off
	s_nop 0
	global_load_dwordx4 v[6:9], v[6:7], off
	v_addc_co_u32_e32 v11, vcc, -1, v223, vcc
	global_load_dwordx4 v[192:195], v[10:11], off
	s_nop 0
	global_load_dwordx4 v[10:13], v[222:223], off offset:-4096
	s_mul_i32 s1, s0, 0x11400
	s_cselect_b64 s[10:11], -1, 0
	s_add_i32 s1, s1, 0
	s_add_i32 s43, s1, s4
	v_add_u32_e32 v0, s43, v236
	s_cmp_gt_u32 s41, s39
	v_add3_u32 v244, s1, v238, v239
	v_add_u32_e32 v245, v0, v237
	s_cbranch_scc1 .LBB0_296
	s_setprio 1
	ds_read_b128 v[144:147], v245
	ds_read_b128 v[196:199], v245 offset:32
	ds_read_b128 v[200:203], v245 offset:64
	ds_read_b128 v[204:207], v245 offset:96
	ds_read_b128 v[208:211], v245 offset:128
	s_waitcnt lgkmcnt(4)
	v_mfma_f32_32x32x16_bf16 v[144:159], v[144:147], v[188:191], 0
	s_waitcnt lgkmcnt(3)
	v_mfma_f32_32x32x16_bf16 v[144:159], v[196:199], v[184:187], v[144:159]
	ds_read_b128 v[196:199], v245 offset:160
	s_waitcnt lgkmcnt(3)
	v_mfma_f32_32x32x16_bf16 v[144:159], v[200:203], v[180:183], v[144:159]
	ds_read_b128 v[200:203], v245 offset:192
	s_waitcnt lgkmcnt(3)
	v_mfma_f32_32x32x16_bf16 v[144:159], v[204:207], v[176:179], v[144:159]
	ds_read_b128 v[204:207], v245 offset:224
	s_waitcnt lgkmcnt(3)
	v_mfma_f32_32x32x16_bf16 v[144:159], v[208:211], v[172:175], v[144:159]
	s_waitcnt lgkmcnt(2)
	v_mfma_f32_32x32x16_bf16 v[144:159], v[196:199], v[168:171], v[144:159]
	s_waitcnt lgkmcnt(1)
	v_mfma_f32_32x32x16_bf16 v[144:159], v[200:203], v[164:167], v[144:159]
	s_waitcnt lgkmcnt(0)
	v_mfma_f32_32x32x16_bf16 v[144:159], v[204:207], v[160:163], v[144:159]
	s_setprio 0
	s_nop 10
	v_pk_mul_f32 v[148:149], v[148:149], s[6:7] op_sel_hi:[1,0]
	v_pk_mul_f32 v[146:147], v[146:147], s[6:7] op_sel_hi:[1,0]
	v_pk_mul_f32 v[144:145], v[144:145], s[6:7] op_sel_hi:[1,0]
	v_pk_mul_f32 v[14:15], v[158:159], s[6:7] op_sel_hi:[1,0]
	v_pk_mul_f32 v[152:153], v[152:153], s[6:7] op_sel_hi:[1,0]
	v_pk_mul_f32 v[150:151], v[150:151], s[6:7] op_sel_hi:[1,0]
	v_max3_f32 v0, v144, v145, v146
	v_max3_f32 v158, v147, v148, v149
	v_pk_mul_f32 v[156:157], v[156:157], s[6:7] op_sel_hi:[1,0]
	v_pk_mul_f32 v[154:155], v[154:155], s[6:7] op_sel_hi:[1,0]
	v_max3_f32 v0, v0, v150, v151
	v_max3_f32 v158, v158, v152, v153
	v_max3_f32 v0, v0, v154, v155
	v_max3_f32 v158, v158, v156, v157
	v_max_f32_e32 v159, v14, v15
	v_max3_f32 v0, v0, v158, v159
	v_mov_b32_e32 v158, v0
	s_nop 1
	v_permlane32_swap_b32 v0, v158
	s_nop 1
	s_nop 0
	v_max_f32_e32 v158, v158, v158
	v_max_f32_e32 v0, v0, v0
	v_max_f32_e32 v0, v0, v158
	v_add_f32_e32 v158, 0x42000000, v243
	v_cmp_gt_f32_e32 vcc, v0, v158
	s_cbranch_vccz .LBB0_295
	v_max_f32_e32 v0, v0, v0
	v_max_f32_e32 v158, v243, v243
	v_max_f32_e32 v158, v158, v0
	v_sub_f32_e32 v0, v243, v158
	v_exp_f32_e32 v0, v0
	v_mov_b32_e32 v243, v158
	v_pk_mul_f32 v[142:143], v[142:143], v[0:1] op_sel_hi:[1,0]
	v_pk_mul_f32 v[140:141], v[140:141], v[0:1] op_sel_hi:[1,0]
	v_pk_mul_f32 v[138:139], v[138:139], v[0:1] op_sel_hi:[1,0]
	v_pk_mul_f32 v[136:137], v[136:137], v[0:1] op_sel_hi:[1,0]
	v_pk_mul_f32 v[134:135], v[134:135], v[0:1] op_sel_hi:[1,0]
	v_pk_mul_f32 v[132:133], v[132:133], v[0:1] op_sel_hi:[1,0]
	v_pk_mul_f32 v[130:131], v[130:131], v[0:1] op_sel_hi:[1,0]
	v_pk_mul_f32 v[128:129], v[128:129], v[0:1] op_sel_hi:[1,0]
	v_pk_mul_f32 v[126:127], v[126:127], v[0:1] op_sel_hi:[1,0]
	v_pk_mul_f32 v[124:125], v[124:125], v[0:1] op_sel_hi:[1,0]
	v_pk_mul_f32 v[122:123], v[122:123], v[0:1] op_sel_hi:[1,0]
	v_pk_mul_f32 v[120:121], v[120:121], v[0:1] op_sel_hi:[1,0]
	v_pk_mul_f32 v[118:119], v[118:119], v[0:1] op_sel_hi:[1,0]
	v_pk_mul_f32 v[116:117], v[116:117], v[0:1] op_sel_hi:[1,0]
	v_pk_mul_f32 v[114:115], v[114:115], v[0:1] op_sel_hi:[1,0]
	v_pk_mul_f32 v[112:113], v[112:113], v[0:1] op_sel_hi:[1,0]
	v_pk_mul_f32 v[110:111], v[110:111], v[0:1] op_sel_hi:[1,0]
	v_pk_mul_f32 v[108:109], v[108:109], v[0:1] op_sel_hi:[1,0]
	v_pk_mul_f32 v[106:107], v[106:107], v[0:1] op_sel_hi:[1,0]
	v_pk_mul_f32 v[104:105], v[104:105], v[0:1] op_sel_hi:[1,0]
	v_pk_mul_f32 v[102:103], v[102:103], v[0:1] op_sel_hi:[1,0]
	v_pk_mul_f32 v[100:101], v[100:101], v[0:1] op_sel_hi:[1,0]
	v_pk_mul_f32 v[98:99], v[98:99], v[0:1] op_sel_hi:[1,0]
	v_pk_mul_f32 v[96:97], v[96:97], v[0:1] op_sel_hi:[1,0]
	v_pk_mul_f32 v[94:95], v[94:95], v[0:1] op_sel_hi:[1,0]
	v_pk_mul_f32 v[92:93], v[92:93], v[0:1] op_sel_hi:[1,0]
	v_pk_mul_f32 v[90:91], v[90:91], v[0:1] op_sel_hi:[1,0]
	v_pk_mul_f32 v[88:89], v[88:89], v[0:1] op_sel_hi:[1,0]
	v_pk_mul_f32 v[86:87], v[86:87], v[0:1] op_sel_hi:[1,0]
	v_pk_mul_f32 v[84:85], v[84:85], v[0:1] op_sel_hi:[1,0]
	v_pk_mul_f32 v[82:83], v[82:83], v[0:1] op_sel_hi:[1,0]
	v_pk_mul_f32 v[80:81], v[80:81], v[0:1] op_sel_hi:[1,0]
	v_pk_mul_f32 v[78:79], v[78:79], v[0:1] op_sel_hi:[1,0]
	v_pk_mul_f32 v[76:77], v[76:77], v[0:1] op_sel_hi:[1,0]
	v_pk_mul_f32 v[74:75], v[74:75], v[0:1] op_sel_hi:[1,0]
	v_pk_mul_f32 v[72:73], v[72:73], v[0:1] op_sel_hi:[1,0]
	v_pk_mul_f32 v[70:71], v[70:71], v[0:1] op_sel_hi:[1,0]
	v_pk_mul_f32 v[68:69], v[68:69], v[0:1] op_sel_hi:[1,0]
	v_pk_mul_f32 v[66:67], v[66:67], v[0:1] op_sel_hi:[1,0]
	v_pk_mul_f32 v[64:65], v[64:65], v[0:1] op_sel_hi:[1,0]
	v_pk_mul_f32 v[62:63], v[62:63], v[0:1] op_sel_hi:[1,0]
	v_pk_mul_f32 v[60:61], v[60:61], v[0:1] op_sel_hi:[1,0]
	v_pk_mul_f32 v[58:59], v[58:59], v[0:1] op_sel_hi:[1,0]
	v_pk_mul_f32 v[56:57], v[56:57], v[0:1] op_sel_hi:[1,0]
	v_pk_mul_f32 v[54:55], v[54:55], v[0:1] op_sel_hi:[1,0]
	v_pk_mul_f32 v[52:53], v[52:53], v[0:1] op_sel_hi:[1,0]
	v_pk_mul_f32 v[50:51], v[50:51], v[0:1] op_sel_hi:[1,0]
	v_pk_mul_f32 v[48:49], v[48:49], v[0:1] op_sel_hi:[1,0]
	v_pk_mul_f32 v[46:47], v[46:47], v[0:1] op_sel_hi:[1,0]
	v_pk_mul_f32 v[44:45], v[44:45], v[0:1] op_sel_hi:[1,0]
	v_pk_mul_f32 v[42:43], v[42:43], v[0:1] op_sel_hi:[1,0]
	v_pk_mul_f32 v[40:41], v[40:41], v[0:1] op_sel_hi:[1,0]
	v_pk_mul_f32 v[38:39], v[38:39], v[0:1] op_sel_hi:[1,0]
	v_pk_mul_f32 v[36:37], v[36:37], v[0:1] op_sel_hi:[1,0]
	v_pk_mul_f32 v[34:35], v[34:35], v[0:1] op_sel_hi:[1,0]
	v_pk_mul_f32 v[32:33], v[32:33], v[0:1] op_sel_hi:[1,0]
	v_pk_mul_f32 v[30:31], v[30:31], v[0:1] op_sel_hi:[1,0]
	v_pk_mul_f32 v[28:29], v[28:29], v[0:1] op_sel_hi:[1,0]
	v_pk_mul_f32 v[26:27], v[26:27], v[0:1] op_sel_hi:[1,0]
	v_pk_mul_f32 v[24:25], v[24:25], v[0:1] op_sel_hi:[1,0]
	v_pk_mul_f32 v[22:23], v[22:23], v[0:1] op_sel_hi:[1,0]
	v_pk_mul_f32 v[20:21], v[20:21], v[0:1] op_sel_hi:[1,0]
	v_pk_mul_f32 v[18:19], v[18:19], v[0:1] op_sel_hi:[1,0]
	v_pk_mul_f32 v[16:17], v[16:17], v[0:1] op_sel_hi:[1,0]
	v_mul_f32_e32 v242, v242, v0

; #define LAS __attribute__((address_space(3)))
; __device__ __forceinline__ float swap_max(float v) { unsigned a = __builtin_bit_cast(unsigned, v), b = a; asm volatile("s_nop 1\n\tv_permlane32_swap_b32 %0, %1\n\ts_nop 1" : "+v"(a), "+v"(b)); return fmaxf(__builtin_bit_cast(float, a), __builtin_bit_cast(float, b)); }
; #define LOAD_V(t) do { _Pragma("unroll") for (int i = 0; i < VCH; ++i) vreg[i] = *(const u32x4*)((const char*)vg + (size_t)((t) * 64 + i * RPPV) * (LD * 2) + vvoff); \
;         if (MODE == 2 && tid < 64) fkreg = X.F2[(size_t)(b * 16 + hd) * SEQ + (t) * 64 + tid]; } while (0)
; template <int MODE>
; __device__ __forceinline__ void attn_unit(LAS unsigned char* lds, const bf16_t* __restrict__ qkvz, bf16_t* __restrict__ A2, const int b, const int hd, const int qb, const AttnX& X, const int tid) {
;     ...
;             for (int kk = 0; kk < 2; ++kk) {
;                 if (active) {
;                     f32x16 S;
; #pragma unroll
;                     for (int i = 0; i < 16; ++i) S[i] = 0.f;
;                     const LAS unsigned char* kb = lds + cur * STG + kbase_off + kk * 32 * PK;
;                     __builtin_amdgcn_s_setprio(1);
; #pragma unroll
;                     for (int s = 0; s < NS; ++s) { const bf16x8 a0 = *(const LAS bf16x8*)(kb + s * 32); S = __builtin_amdgcn_mfma_f32_32x32x16_bf16(a0, qf[s], S, 0, 0, 0); }
;                     __builtin_amdgcn_s_setprio(0);
;                     S = S * c2;
;                     float a0 = fmaxf(fmaxf(S[0], S[1]), S[2]), a1 = fmaxf(fmaxf(S[3], S[4]), S[5]);
; #pragma unroll
;                     for (int i = 6; i < 14; i += 4) { a0 = fmaxf(fmaxf(a0, S[i]), S[i + 1]); a1 = fmaxf(fmaxf(a1, S[i + 2]), S[i + 3]); }
;                     const float mx = swap_max(fmaxf(fmaxf(a0, a1), fmaxf(S[14], S[15])));
;                     const float m_new = fmaxf(m_run, mx);
;                     if (__any(mx > m_run + RESCALE_THR)) {
;                         const float alpha = __builtin_amdgcn_exp2f(m_run - m_new);
;                         l_run *= alpha;
; #pragma unroll
;                         for (int d = 0; d < NDT; ++d) O[d] = O[d] * alpha;
;                         m_run = m_new;
;                     }
;     ...
;                 if (kk == 0) { if (has_next) { STORE_K(nxt); LOAD_V(TILE(n + 1)); } }
.LBB0_296:
	v_add_co_u32_e32 v14, vcc, 0xfff40000, v222
	s_xor_b32 s0, s0, 1
	s_nop 0
	v_addc_co_u32_e32 v15, vcc, -1, v223, vcc
	v_add_co_u32_e32 v144, vcc, 0xfff80000, v222
	s_mul_i32 s0, s0, 0x11400
	s_nop 0
	v_addc_co_u32_e32 v145, vcc, -1, v223, vcc
	global_load_dwordx4 v[196:199], v[14:15], off
	global_load_dwordx4 v[200:203], v[144:145], off
	v_add_co_u32_e32 v14, vcc, 0xfffc0000, v222
	v_add_u32_e32 v0, s0, v234
	s_nop 0
	v_addc_co_u32_e32 v15, vcc, -1, v223, vcc
	global_load_dwordx4 v[204:207], v[14:15], off
	global_load_dwordx4 v[208:211], v[222:223], off
	s_andn2_b64 vcc, exec, s[10:11]
	s_waitcnt vmcnt(7)
	ds_write_b128 v0, v[2:5]
	s_waitcnt vmcnt(6)
	ds_write_b128 v0, v[6:9] offset:8448
	s_waitcnt vmcnt(5)
	ds_write_b128 v0, v[192:195] offset:16896
	s_waitcnt vmcnt(4)
	ds_write_b128 v0, v[10:13] offset:25344
	s_cbranch_vccnz .LBB0_291
	s_setprio 1
	ds_read_b128 v[2:5], v245 offset:16896
	ds_read_b128 v[6:9], v245 offset:16928
	ds_read_b128 v[10:13], v245 offset:16960
	ds_read_b128 v[192:195], v245 offset:16992
	s_waitcnt lgkmcnt(3)
	v_mfma_f32_32x32x16_bf16 v[144:159], v[2:5], v[188:191], 0
	ds_read_b128 v[2:5], v245 offset:17024
	s_waitcnt lgkmcnt(3)
	v_mfma_f32_32x32x16_bf16 v[144:159], v[6:9], v[184:187], v[144:159]
	ds_read_b128 v[6:9], v245 offset:17056
	s_waitcnt lgkmcnt(3)
	v_mfma_f32_32x32x16_bf16 v[144:159], v[10:13], v[180:183], v[144:159]
	ds_read_b128 v[10:13], v245 offset:17088
	s_waitcnt lgkmcnt(3)
	v_mfma_f32_32x32x16_bf16 v[144:159], v[192:195], v[176:179], v[144:159]
	ds_read_b128 v[192:195], v245 offset:17120
	s_waitcnt lgkmcnt(3)
	v_mfma_f32_32x32x16_bf16 v[144:159], v[2:5], v[172:175], v[144:159]
	s_waitcnt lgkmcnt(2)
	v_mfma_f32_32x32x16_bf16 v[144:159], v[6:9], v[168:171], v[144:159]
	s_waitcnt lgkmcnt(1)
	v_mfma_f32_32x32x16_bf16 v[144:159], v[10:13], v[164:167], v[144:159]
	s_waitcnt lgkmcnt(0)
	v_mfma_f32_32x32x16_bf16 v[144:159], v[192:195], v[160:163], v[144:159]
	s_setprio 0
	s_nop 10
	v_pk_mul_f32 v[12:13], v[148:149], s[6:7] op_sel_hi:[1,0]
	v_pk_mul_f32 v[146:147], v[146:147], s[6:7] op_sel_hi:[1,0]
	v_pk_mul_f32 v[14:15], v[144:145], s[6:7] op_sel_hi:[1,0]
	v_pk_mul_f32 v[8:9], v[152:153], s[6:7] op_sel_hi:[1,0]
	v_pk_mul_f32 v[10:11], v[150:151], s[6:7] op_sel_hi:[1,0]
	v_max3_f32 v0, v14, v15, v146
	v_max3_f32 v144, v147, v12, v13
	v_pk_mul_f32 v[2:3], v[158:159], s[6:7] op_sel_hi:[1,0]
	v_pk_mul_f32 v[4:5], v[156:157], s[6:7] op_sel_hi:[1,0]
	v_pk_mul_f32 v[6:7], v[154:155], s[6:7] op_sel_hi:[1,0]
	v_max3_f32 v0, v0, v10, v11
	v_max3_f32 v144, v144, v8, v9
	v_max3_f32 v0, v0, v6, v7
	v_max3_f32 v144, v144, v4, v5
	v_max_f32_e32 v145, v2, v3
	v_max3_f32 v0, v0, v144, v145
	v_mov_b32_e32 v144, v0
	s_nop 1
	v_permlane32_swap_b32 v0, v144
	s_nop 1
	s_nop 0
	v_max_f32_e32 v144, v144, v144
	v_max_f32_e32 v0, v0, v0
	v_max_f32_e32 v0, v0, v144
	v_add_f32_e32 v144, 0x42000000, v243
	v_cmp_gt_f32_e32 vcc, v0, v144
	s_cbranch_vccz .LBB0_290
	v_max_f32_e32 v0, v0, v0
	v_max_f32_e32 v144, v243, v243
	v_max_f32_e32 v144, v144, v0
	v_sub_f32_e32 v0, v243, v144
	v_exp_f32_e32 v0, v0
	v_mov_b32_e32 v243, v144
	v_pk_mul_f32 v[142:143], v[142:143], v[0:1] op_sel_hi:[1,0]
	v_pk_mul_f32 v[140:141], v[140:141], v[0:1] op_sel_hi:[1,0]
	v_pk_mul_f32 v[138:139], v[138:139], v[0:1] op_sel_hi:[1,0]
	v_pk_mul_f32 v[136:137], v[136:137], v[0:1] op_sel_hi:[1,0]
	v_pk_mul_f32 v[134:135], v[134:135], v[0:1] op_sel_hi:[1,0]
	v_pk_mul_f32 v[132:133], v[132:133], v[0:1] op_sel_hi:[1,0]
	v_pk_mul_f32 v[130:131], v[130:131], v[0:1] op_sel_hi:[1,0]
	v_pk_mul_f32 v[128:129], v[128:129], v[0:1] op_sel_hi:[1,0]
	v_pk_mul_f32 v[126:127], v[126:127], v[0:1] op_sel_hi:[1,0]
	v_pk_mul_f32 v[124:125], v[124:125], v[0:1] op_sel_hi:[1,0]
	v_pk_mul_f32 v[122:123], v[122:123], v[0:1] op_sel_hi:[1,0]
	v_pk_mul_f32 v[120:121], v[120:121], v[0:1] op_sel_hi:[1,0]
	v_pk_mul_f32 v[118:119], v[118:119], v[0:1] op_sel_hi:[1,0]
	v_pk_mul_f32 v[116:117], v[116:117], v[0:1] op_sel_hi:[1,0]
	v_pk_mul_f32 v[114:115], v[114:115], v[0:1] op_sel_hi:[1,0]
	v_pk_mul_f32 v[112:113], v[112:113], v[0:1] op_sel_hi:[1,0]
	v_pk_mul_f32 v[110:111], v[110:111], v[0:1] op_sel_hi:[1,0]
	v_pk_mul_f32 v[108:109], v[108:109], v[0:1] op_sel_hi:[1,0]
	v_pk_mul_f32 v[106:107], v[106:107], v[0:1] op_sel_hi:[1,0]
	v_pk_mul_f32 v[104:105], v[104:105], v[0:1] op_sel_hi:[1,0]
	v_pk_mul_f32 v[102:103], v[102:103], v[0:1] op_sel_hi:[1,0]
	v_pk_mul_f32 v[100:101], v[100:101], v[0:1] op_sel_hi:[1,0]
	v_pk_mul_f32 v[98:99], v[98:99], v[0:1] op_sel_hi:[1,0]
	v_pk_mul_f32 v[96:97], v[96:97], v[0:1] op_sel_hi:[1,0]
	v_pk_mul_f32 v[94:95], v[94:95], v[0:1] op_sel_hi:[1,0]
	v_pk_mul_f32 v[92:93], v[92:93], v[0:1] op_sel_hi:[1,0]
	v_pk_mul_f32 v[90:91], v[90:91], v[0:1] op_sel_hi:[1,0]
	v_pk_mul_f32 v[88:89], v[88:89], v[0:1] op_sel_hi:[1,0]
	v_pk_mul_f32 v[86:87], v[86:87], v[0:1] op_sel_hi:[1,0]
	v_pk_mul_f32 v[84:85], v[84:85], v[0:1] op_sel_hi:[1,0]
	v_pk_mul_f32 v[82:83], v[82:83], v[0:1] op_sel_hi:[1,0]
	v_pk_mul_f32 v[80:81], v[80:81], v[0:1] op_sel_hi:[1,0]
	v_pk_mul_f32 v[78:79], v[78:79], v[0:1] op_sel_hi:[1,0]
	v_pk_mul_f32 v[76:77], v[76:77], v[0:1] op_sel_hi:[1,0]
	v_pk_mul_f32 v[74:75], v[74:75], v[0:1] op_sel_hi:[1,0]
	v_pk_mul_f32 v[72:73], v[72:73], v[0:1] op_sel_hi:[1,0]
	v_pk_mul_f32 v[70:71], v[70:71], v[0:1] op_sel_hi:[1,0]
	v_pk_mul_f32 v[68:69], v[68:69], v[0:1] op_sel_hi:[1,0]
	v_pk_mul_f32 v[66:67], v[66:67], v[0:1] op_sel_hi:[1,0]
	v_pk_mul_f32 v[64:65], v[64:65], v[0:1] op_sel_hi:[1,0]
	v_pk_mul_f32 v[62:63], v[62:63], v[0:1] op_sel_hi:[1,0]
	v_pk_mul_f32 v[60:61], v[60:61], v[0:1] op_sel_hi:[1,0]
	v_pk_mul_f32 v[58:59], v[58:59], v[0:1] op_sel_hi:[1,0]
	v_pk_mul_f32 v[56:57], v[56:57], v[0:1] op_sel_hi:[1,0]
	v_pk_mul_f32 v[54:55], v[54:55], v[0:1] op_sel_hi:[1,0]
	v_pk_mul_f32 v[52:53], v[52:53], v[0:1] op_sel_hi:[1,0]
	v_pk_mul_f32 v[50:51], v[50:51], v[0:1] op_sel_hi:[1,0]
	v_pk_mul_f32 v[48:49], v[48:49], v[0:1] op_sel_hi:[1,0]
	v_pk_mul_f32 v[46:47], v[46:47], v[0:1] op_sel_hi:[1,0]
	v_pk_mul_f32 v[44:45], v[44:45], v[0:1] op_sel_hi:[1,0]
	v_pk_mul_f32 v[42:43], v[42:43], v[0:1] op_sel_hi:[1,0]
	v_pk_mul_f32 v[40:41], v[40:41], v[0:1] op_sel_hi:[1,0]
	v_pk_mul_f32 v[38:39], v[38:39], v[0:1] op_sel_hi:[1,0]
	v_pk_mul_f32 v[36:37], v[36:37], v[0:1] op_sel_hi:[1,0]
	v_pk_mul_f32 v[34:35], v[34:35], v[0:1] op_sel_hi:[1,0]
	v_pk_mul_f32 v[32:33], v[32:33], v[0:1] op_sel_hi:[1,0]
	v_pk_mul_f32 v[30:31], v[30:31], v[0:1] op_sel_hi:[1,0]
	v_pk_mul_f32 v[28:29], v[28:29], v[0:1] op_sel_hi:[1,0]
	v_pk_mul_f32 v[26:27], v[26:27], v[0:1] op_sel_hi:[1,0]
	v_pk_mul_f32 v[24:25], v[24:25], v[0:1] op_sel_hi:[1,0]
	v_pk_mul_f32 v[22:23], v[22:23], v[0:1] op_sel_hi:[1,0]
	v_pk_mul_f32 v[20:21], v[20:21], v[0:1] op_sel_hi:[1,0]
	v_pk_mul_f32 v[18:19], v[18:19], v[0:1] op_sel_hi:[1,0]
	v_pk_mul_f32 v[16:17], v[16:17], v[0:1] op_sel_hi:[1,0]
	v_mul_f32_e32 v242, v242, v0
	s_branch .LBB0_290

; __device__ __forceinline__ unsigned pk2(float lo, float hi) { f32x2 v = {lo, hi}; bf16x2_t b = __builtin_convertvector(v, bf16x2_t); return __builtin_bit_cast(unsigned, b); }
; __device__ __forceinline__ float silu_f(float z) { return z * __builtin_amdgcn_rcpf(1.0f + __expf(-z)); }
;     __device__ __forceinline__ void operator()(const f32x4 (&acc)[2][2][4][2], const Unit& u, int wr, int wc, int fr, int fq) const {
;         const int row0 = u.pm * BM + wr * 64 + fr; const int col0 = u.pn * BM + wc * 32 + 8 * fq;
; #pragma unroll
;         for (int bj = 0; bj < 2; ++bj) {
;             const f32x4 s0 = *(const f32x4*)(ps + col0 + bj * HALF), s1 = *(const f32x4*)(ps + col0 + bj * HALF + 4);
; #pragma unroll
;             for (int ai = 0; ai < 2; ++ai)
; #pragma unroll
;                 for (int m = 0; m < 4; ++m) { const size_t r = (size_t)(row0 + ai * HALF + m * 16);
;                     const u32x4 zz = *(const u32x4*)(Z + r * ldz + col0 + bj * HALF);
;                     const f32x4 v0 = acc[ai][bj][m][0], v1 = acc[ai][bj][m][1];
;                     u32x4 w;
;                     w.x = pk2(v0[0] * s0[0] * silu_f(bflo(zz.x)), v0[1] * s0[1] * silu_f(bfhi(zz.x)));
;                     w.y = pk2(v0[2] * s0[2] * silu_f(bflo(zz.y)), v0[3] * s0[3] * silu_f(bfhi(zz.y)));
;                     w.z = pk2(v1[0] * s1[0] * silu_f(bflo(zz.z)), v1[1] * s1[1] * silu_f(bfhi(zz.z)));
;                     w.w = pk2(v1[2] * s1[2] * silu_f(bflo(zz.w)), v1[3] * s1[3] * silu_f(bfhi(zz.w)));
;                     *(u32x4*)(O + r * ldc + col0 + bj * HALF) = w; } }
.LBB0_1428:
	v_lshl_add_u32 v168, s20, 8, v172
	v_lshl_or_b32 v136, s0, 8, v174
	v_ashrrev_i32_e32 v169, 31, v168
	v_ashrrev_i32_e32 v137, 31, v136
	v_lshlrev_b64 v[138:139], 13, v[168:169]
	v_lshl_add_u64 v[138:139], s[6:7], 0, v[138:139]
	v_lshlrev_b64 v[166:167], 1, v[136:137]
	v_lshl_add_u64 v[164:165], v[136:137], 2, s[76:77]
	v_lshl_add_u64 v[140:141], v[138:139], 0, v[166:167]
	global_load_dwordx4 v[128:131], v[164:165], off offset:16
	global_load_dwordx4 v[132:135], v[164:165], off
	global_load_dwordx4 v[136:139], v[140:141], off
	v_lshlrev_b64 v[142:143], 12, v[168:169]
	v_or_b32_e32 v170, 16, v168
	v_ashrrev_i32_e32 v171, 31, v170
	v_lshl_add_u64 v[142:143], s[94:95], 0, v[142:143]
	v_lshlrev_b64 v[162:163], 13, v[170:171]
	v_lshl_add_u64 v[160:161], v[142:143], 0, v[166:167]
	v_lshl_add_u64 v[142:143], s[6:7], 0, v[162:163]
	v_lshl_add_u64 v[162:163], v[142:143], 0, v[166:167]
	global_load_dwordx4 v[140:143], v[140:141], off offset:256
	s_andn2_b64 vcc, exec, s[2:3]
	s_mov_b64 s[2:3], -1
	s_waitcnt vmcnt(0)
	v_pk_mul_f32 v[122:123], v[122:123], v[130:131]
	v_pk_mul_f32 v[126:127], v[126:127], v[134:135]
	v_lshlrev_b32_e32 v178, 16, v136
	v_and_b32_e32 v179, 0xffff0000, v136
	v_lshlrev_b32_e32 v136, 16, v137
	v_and_b32_e32 v137, 0xffff0000, v137
	v_lshlrev_b32_e32 v180, 16, v138
	v_and_b32_e32 v181, 0xffff0000, v138
	v_lshlrev_b32_e32 v138, 16, v139
	v_and_b32_e32 v139, 0xffff0000, v139
	v_mul_f32_e32 v169, 0xbfb8aa3b, v178
	v_mul_f32_e32 v182, 0xbfb8aa3b, v179
	v_mul_f32_e32 v183, 0xbfb8aa3b, v136
	v_mul_f32_e32 v184, 0xbfb8aa3b, v137
	v_mul_f32_e32 v185, 0xbfb8aa3b, v180
	v_mul_f32_e32 v186, 0xbfb8aa3b, v181
	v_mul_f32_e32 v187, 0xbfb8aa3b, v138
	v_mul_f32_e32 v188, 0xbfb8aa3b, v139
	v_exp_f32_e32 v169, v169
	v_exp_f32_e32 v182, v182
	v_exp_f32_e32 v183, v183
	v_exp_f32_e32 v184, v184
	v_exp_f32_e32 v185, v185
	v_exp_f32_e32 v186, v186
	v_exp_f32_e32 v187, v187
	v_exp_f32_e32 v188, v188
	v_add_f32_e32 v169, 1.0, v169
	v_add_f32_e32 v189, 1.0, v182
	v_add_f32_e32 v190, 1.0, v183
	v_add_f32_e32 v191, 1.0, v184
	v_add_f32_e32 v192, 1.0, v185
	v_add_f32_e32 v193, 1.0, v186
	v_add_f32_e32 v194, 1.0, v187
	v_add_f32_e32 v195, 1.0, v188
	v_rcp_f32_e32 v182, v169
	v_rcp_f32_e32 v183, v189
	v_rcp_f32_e32 v184, v190
	v_rcp_f32_e32 v185, v191
	v_rcp_f32_e32 v186, v192
	v_rcp_f32_e32 v187, v193
	v_rcp_f32_e32 v188, v194
	v_rcp_f32_e32 v189, v195
	v_pk_mul_f32 v[124:125], v[124:125], v[132:133]
	v_pk_mul_f32 v[120:121], v[120:121], v[128:129]
	v_pk_mul_f32 v[178:179], v[182:183], v[178:179]
	v_pk_mul_f32 v[136:137], v[184:185], v[136:137]
	v_pk_mul_f32 v[180:181], v[186:187], v[180:181]
	v_pk_mul_f32 v[138:139], v[188:189], v[138:139]
	v_pk_mul_f32 v[124:125], v[124:125], v[178:179]
	v_pk_mul_f32 v[126:127], v[126:127], v[136:137]
	v_pk_mul_f32 v[136:137], v[120:121], v[180:181]
	v_pk_mul_f32 v[138:139], v[122:123], v[138:139]
	v_cvt_pk_bf16_f32 v120, v124, v125
	v_cvt_pk_bf16_f32 v121, v126, v127
	v_cvt_pk_bf16_f32 v122, v136, v137
	v_cvt_pk_bf16_f32 v123, v138, v139
	global_store_dwordx4 v[160:161], v[120:123], off
	global_load_dwordx4 v[124:127], v[162:163], off
	v_or_b32_e32 v136, 32, v168
	v_lshlrev_b64 v[120:121], 12, v[170:171]
	v_ashrrev_i32_e32 v137, 31, v136
	v_pk_mul_f32 v[118:119], v[118:119], v[134:135]
	v_pk_mul_f32 v[116:117], v[116:117], v[132:133]
	v_pk_mul_f32 v[114:115], v[114:115], v[130:131]
	v_pk_mul_f32 v[112:113], v[112:113], v[128:129]
	v_lshlrev_b64 v[122:123], 13, v[136:137]
	v_lshl_add_u64 v[120:121], s[94:95], 0, v[120:121]
	v_lshl_add_u64 v[122:123], s[6:7], 0, v[122:123]
	v_lshl_add_u64 v[120:121], v[120:121], 0, v[166:167]
	v_lshl_add_u64 v[122:123], v[122:123], 0, v[166:167]
	v_pk_mul_f32 v[110:111], v[110:111], v[134:135]
	v_pk_mul_f32 v[108:109], v[108:109], v[132:133]
	v_pk_mul_f32 v[106:107], v[106:107], v[130:131]
	v_pk_mul_f32 v[104:105], v[104:105], v[128:129]
	v_pk_mul_f32 v[102:103], v[102:103], v[134:135]
	v_pk_mul_f32 v[100:101], v[100:101], v[132:133]
	v_pk_mul_f32 v[98:99], v[98:99], v[130:131]
	v_pk_mul_f32 v[96:97], v[96:97], v[128:129]
	v_pk_mul_f32 v[94:95], v[94:95], v[134:135]
	v_pk_mul_f32 v[92:93], v[92:93], v[132:133]
	v_pk_mul_f32 v[90:91], v[90:91], v[130:131]
	v_pk_mul_f32 v[88:89], v[88:89], v[128:129]
	v_pk_mul_f32 v[86:87], v[86:87], v[134:135]
	v_pk_mul_f32 v[84:85], v[84:85], v[132:133]
	v_pk_mul_f32 v[82:83], v[82:83], v[130:131]
	v_pk_mul_f32 v[80:81], v[80:81], v[128:129]
	v_pk_mul_f32 v[78:79], v[78:79], v[134:135]
	v_pk_mul_f32 v[76:77], v[76:77], v[132:133]
	v_pk_mul_f32 v[74:75], v[74:75], v[130:131]
	v_pk_mul_f32 v[72:73], v[72:73], v[128:129]
	v_pk_mul_f32 v[70:71], v[70:71], v[134:135]
	v_pk_mul_f32 v[68:69], v[68:69], v[132:133]
	v_pk_mul_f32 v[66:67], v[66:67], v[130:131]
	v_pk_mul_f32 v[64:65], v[64:65], v[128:129]
	s_waitcnt vmcnt(0)
; __device__ __forceinline__ unsigned pk2(float lo, float hi) { f32x2 v = {lo, hi}; bf16x2_t b = __builtin_convertvector(v, bf16x2_t); return __builtin_bit_cast(unsigned, b); }
; __device__ __forceinline__ float silu_f(float z) { return z * __builtin_amdgcn_rcpf(1.0f + __expf(-z)); }
;     __device__ __forceinline__ void operator()(const f32x4 (&acc)[2][2][4][2], const Unit& u, int wr, int wc, int fr, int fq) const {
;     ...
;                 for (int m = 0; m < 4; ++m) { const size_t r = (size_t)(row0 + ai * HALF + m * 16);
;                     const u32x4 zz = *(const u32x4*)(Z + r * ldz + col0 + bj * HALF);
;                     const f32x4 v0 = acc[ai][bj][m][0], v1 = acc[ai][bj][m][1];
;                     u32x4 w;
;                     w.x = pk2(v0[0] * s0[0] * silu_f(bflo(zz.x)), v0[1] * s0[1] * silu_f(bfhi(zz.x)));
;                     w.y = pk2(v0[2] * s0[2] * silu_f(bflo(zz.y)), v0[3] * s0[3] * silu_f(bfhi(zz.y)));
;                     w.z = pk2(v1[0] * s1[0] * silu_f(bflo(zz.z)), v1[1] * s1[1] * silu_f(bfhi(zz.z)));
;                     w.w = pk2(v1[2] * s1[2] * silu_f(bflo(zz.w)), v1[3] * s1[3] * silu_f(bfhi(zz.w)));
;                     *(u32x4*)(O + r * ldc + col0 + bj * HALF) = w; } }
	v_lshlrev_b32_e32 v138, 16, v124
	v_and_b32_e32 v139, 0xffff0000, v124
	v_lshlrev_b32_e32 v124, 16, v125
	v_and_b32_e32 v125, 0xffff0000, v125
	v_lshlrev_b32_e32 v170, 16, v126
	v_and_b32_e32 v171, 0xffff0000, v126
	v_lshlrev_b32_e32 v126, 16, v127
	v_and_b32_e32 v127, 0xffff0000, v127
	v_mul_f32_e32 v169, 0xbfb8aa3b, v138
	v_mul_f32_e32 v178, 0xbfb8aa3b, v139
	v_mul_f32_e32 v179, 0xbfb8aa3b, v124
	v_mul_f32_e32 v180, 0xbfb8aa3b, v125
	v_mul_f32_e32 v181, 0xbfb8aa3b, v170
	v_mul_f32_e32 v182, 0xbfb8aa3b, v171
	v_mul_f32_e32 v183, 0xbfb8aa3b, v126
	v_mul_f32_e32 v184, 0xbfb8aa3b, v127
	v_exp_f32_e32 v169, v169
	v_exp_f32_e32 v178, v178
	v_exp_f32_e32 v179, v179
	v_exp_f32_e32 v180, v180
	v_exp_f32_e32 v181, v181
	v_exp_f32_e32 v182, v182
	v_exp_f32_e32 v183, v183
	v_exp_f32_e32 v184, v184
	v_add_f32_e32 v169, 1.0, v169
	v_add_f32_e32 v185, 1.0, v178
	v_add_f32_e32 v186, 1.0, v179
	v_add_f32_e32 v187, 1.0, v180
	v_add_f32_e32 v188, 1.0, v181
	v_add_f32_e32 v189, 1.0, v182
	v_add_f32_e32 v190, 1.0, v183
	v_add_f32_e32 v191, 1.0, v184
	v_rcp_f32_e32 v178, v169
	v_rcp_f32_e32 v179, v185
	v_rcp_f32_e32 v180, v186
	v_rcp_f32_e32 v181, v187
	v_rcp_f32_e32 v182, v188
	v_rcp_f32_e32 v183, v189
	v_rcp_f32_e32 v184, v190
	v_rcp_f32_e32 v185, v191
	v_pk_mul_f32 v[138:139], v[178:179], v[138:139]
	v_pk_mul_f32 v[124:125], v[180:181], v[124:125]
	v_pk_mul_f32 v[170:171], v[182:183], v[170:171]
	v_pk_mul_f32 v[126:127], v[184:185], v[126:127]
	v_pk_mul_f32 v[116:117], v[116:117], v[138:139]
	v_pk_mul_f32 v[118:119], v[118:119], v[124:125]
	v_pk_mul_f32 v[124:125], v[112:113], v[170:171]
	v_pk_mul_f32 v[126:127], v[114:115], v[126:127]
	v_cvt_pk_bf16_f32 v112, v116, v117
	v_cvt_pk_bf16_f32 v113, v118, v119
	v_cvt_pk_bf16_f32 v114, v124, v125
	v_cvt_pk_bf16_f32 v115, v126, v127
	global_load_dwordx4 v[116:119], v[122:123], off
	global_store_dwordx4 v[120:121], v[112:115], off
	s_nop 1
	v_or_b32_e32 v124, 48, v168
	v_lshlrev_b64 v[112:113], 12, v[136:137]
	v_ashrrev_i32_e32 v125, 31, v124
	v_lshlrev_b64 v[114:115], 13, v[124:125]
	v_lshl_add_u64 v[112:113], s[94:95], 0, v[112:113]
	v_lshl_add_u64 v[114:115], s[6:7], 0, v[114:115]
	v_lshl_add_u64 v[112:113], v[112:113], 0, v[166:167]
	v_lshl_add_u64 v[114:115], v[114:115], 0, v[166:167]
	s_waitcnt vmcnt(1)
	v_lshlrev_b32_e32 v126, 16, v116
	v_and_b32_e32 v127, 0xffff0000, v116
	v_lshlrev_b32_e32 v116, 16, v117
	v_and_b32_e32 v117, 0xffff0000, v117
	v_lshlrev_b32_e32 v136, 16, v118
	v_and_b32_e32 v137, 0xffff0000, v118
	v_lshlrev_b32_e32 v118, 16, v119
	v_and_b32_e32 v119, 0xffff0000, v119
	v_mul_f32_e32 v138, 0xbfb8aa3b, v126
	v_mul_f32_e32 v139, 0xbfb8aa3b, v127
	v_mul_f32_e32 v169, 0xbfb8aa3b, v116
	v_mul_f32_e32 v170, 0xbfb8aa3b, v117
	v_mul_f32_e32 v171, 0xbfb8aa3b, v136
	v_mul_f32_e32 v178, 0xbfb8aa3b, v137
	v_mul_f32_e32 v179, 0xbfb8aa3b, v118
	v_mul_f32_e32 v180, 0xbfb8aa3b, v119
	v_exp_f32_e32 v138, v138
	v_exp_f32_e32 v139, v139
	v_exp_f32_e32 v169, v169
	v_exp_f32_e32 v170, v170
	v_exp_f32_e32 v171, v171
	v_exp_f32_e32 v178, v178
	v_exp_f32_e32 v179, v179
	v_exp_f32_e32 v180, v180
	v_add_f32_e32 v138, 1.0, v138
	v_add_f32_e32 v139, 1.0, v139
	v_add_f32_e32 v169, 1.0, v169
	v_add_f32_e32 v181, 1.0, v170
	v_add_f32_e32 v182, 1.0, v171
	v_add_f32_e32 v183, 1.0, v178
	v_add_f32_e32 v184, 1.0, v179
	v_add_f32_e32 v185, 1.0, v180
	v_rcp_f32_e32 v138, v138
	v_rcp_f32_e32 v139, v139
	v_rcp_f32_e32 v170, v169
	v_rcp_f32_e32 v171, v181
	v_rcp_f32_e32 v178, v182
	v_rcp_f32_e32 v179, v183
	v_rcp_f32_e32 v180, v184
	v_rcp_f32_e32 v181, v185
	v_pk_mul_f32 v[126:127], v[138:139], v[126:127]
	v_pk_mul_f32 v[116:117], v[170:171], v[116:117]
	v_pk_mul_f32 v[136:137], v[178:179], v[136:137]
	v_pk_mul_f32 v[118:119], v[180:181], v[118:119]
	v_pk_mul_f32 v[108:109], v[108:109], v[126:127]
	v_pk_mul_f32 v[110:111], v[110:111], v[116:117]
	v_pk_mul_f32 v[116:117], v[104:105], v[136:137]
	v_pk_mul_f32 v[118:119], v[106:107], v[118:119]
	v_cvt_pk_bf16_f32 v104, v108, v109
	v_cvt_pk_bf16_f32 v105, v110, v111
	v_cvt_pk_bf16_f32 v106, v116, v117
	v_cvt_pk_bf16_f32 v107, v118, v119
	global_load_dwordx4 v[108:111], v[114:115], off
	global_store_dwordx4 v[112:113], v[104:107], off
	s_nop 1
	v_add_u32_e32 v116, 0x80, v168
	v_lshlrev_b64 v[104:105], 12, v[124:125]
	v_ashrrev_i32_e32 v117, 31, v116
	v_lshlrev_b64 v[106:107], 13, v[116:117]
	v_lshl_add_u64 v[104:105], s[94:95], 0, v[104:105]
	v_lshl_add_u64 v[106:107], s[6:7], 0, v[106:107]
	v_lshl_add_u64 v[104:105], v[104:105], 0, v[166:167]
	v_lshl_add_u64 v[106:107], v[106:107], 0, v[166:167]
	s_waitcnt vmcnt(1)
; __device__ __forceinline__ unsigned pk2(float lo, float hi) { f32x2 v = {lo, hi}; bf16x2_t b = __builtin_convertvector(v, bf16x2_t); return __builtin_bit_cast(unsigned, b); }
; __device__ __forceinline__ float silu_f(float z) { return z * __builtin_amdgcn_rcpf(1.0f + __expf(-z)); }
;     __device__ __forceinline__ void operator()(const f32x4 (&acc)[2][2][4][2], const Unit& u, int wr, int wc, int fr, int fq) const {
;     ...
;                 for (int m = 0; m < 4; ++m) { const size_t r = (size_t)(row0 + ai * HALF + m * 16);
;                     const u32x4 zz = *(const u32x4*)(Z + r * ldz + col0 + bj * HALF);
;                     const f32x4 v0 = acc[ai][bj][m][0], v1 = acc[ai][bj][m][1];
;                     u32x4 w;
;                     w.x = pk2(v0[0] * s0[0] * silu_f(bflo(zz.x)), v0[1] * s0[1] * silu_f(bfhi(zz.x)));
;                     w.y = pk2(v0[2] * s0[2] * silu_f(bflo(zz.y)), v0[3] * s0[3] * silu_f(bfhi(zz.y)));
;                     w.z = pk2(v1[0] * s1[0] * silu_f(bflo(zz.z)), v1[1] * s1[1] * silu_f(bfhi(zz.z)));
;                     w.w = pk2(v1[2] * s1[2] * silu_f(bflo(zz.w)), v1[3] * s1[3] * silu_f(bfhi(zz.w)));
;                     *(u32x4*)(O + r * ldc + col0 + bj * HALF) = w; } }
	v_lshlrev_b32_e32 v118, 16, v108
	v_and_b32_e32 v119, 0xffff0000, v108
	v_lshlrev_b32_e32 v108, 16, v109
	v_and_b32_e32 v109, 0xffff0000, v109
	v_lshlrev_b32_e32 v124, 16, v110
	v_and_b32_e32 v125, 0xffff0000, v110
	v_lshlrev_b32_e32 v110, 16, v111
	v_and_b32_e32 v111, 0xffff0000, v111
	v_mul_f32_e32 v126, 0xbfb8aa3b, v118
	v_mul_f32_e32 v127, 0xbfb8aa3b, v119
	v_mul_f32_e32 v136, 0xbfb8aa3b, v108
	v_mul_f32_e32 v137, 0xbfb8aa3b, v109
	v_mul_f32_e32 v138, 0xbfb8aa3b, v124
	v_mul_f32_e32 v139, 0xbfb8aa3b, v125
	v_mul_f32_e32 v169, 0xbfb8aa3b, v110
	v_mul_f32_e32 v170, 0xbfb8aa3b, v111
	v_exp_f32_e32 v126, v126
	v_exp_f32_e32 v127, v127
	v_exp_f32_e32 v136, v136
	v_exp_f32_e32 v137, v137
	v_exp_f32_e32 v138, v138
	v_exp_f32_e32 v139, v139
	v_exp_f32_e32 v169, v169
	v_exp_f32_e32 v170, v170
	v_add_f32_e32 v126, 1.0, v126
	v_add_f32_e32 v127, 1.0, v127
	v_add_f32_e32 v136, 1.0, v136
	v_add_f32_e32 v137, 1.0, v137
	v_add_f32_e32 v138, 1.0, v138
	v_add_f32_e32 v139, 1.0, v139
	v_add_f32_e32 v169, 1.0, v169
	v_add_f32_e32 v171, 1.0, v170
	v_rcp_f32_e32 v126, v126
	v_rcp_f32_e32 v127, v127
	v_rcp_f32_e32 v136, v136
	v_rcp_f32_e32 v137, v137
	v_rcp_f32_e32 v138, v138
	v_rcp_f32_e32 v139, v139
	v_rcp_f32_e32 v170, v169
	v_rcp_f32_e32 v171, v171
	v_pk_mul_f32 v[118:119], v[126:127], v[118:119]
	v_pk_mul_f32 v[108:109], v[136:137], v[108:109]
	v_pk_mul_f32 v[124:125], v[138:139], v[124:125]
	v_pk_mul_f32 v[110:111], v[170:171], v[110:111]
	v_pk_mul_f32 v[100:101], v[100:101], v[118:119]
	v_pk_mul_f32 v[102:103], v[102:103], v[108:109]
	v_pk_mul_f32 v[108:109], v[96:97], v[124:125]
	v_pk_mul_f32 v[110:111], v[98:99], v[110:111]
	v_cvt_pk_bf16_f32 v96, v100, v101
	v_cvt_pk_bf16_f32 v97, v102, v103
	v_cvt_pk_bf16_f32 v98, v108, v109
	v_cvt_pk_bf16_f32 v99, v110, v111
	global_load_dwordx4 v[100:103], v[106:107], off
	global_store_dwordx4 v[104:105], v[96:99], off
	s_nop 1
	v_add_u32_e32 v108, 0x90, v168
	v_lshlrev_b64 v[96:97], 12, v[116:117]
	v_ashrrev_i32_e32 v109, 31, v108
	v_lshlrev_b64 v[98:99], 13, v[108:109]
	v_lshl_add_u64 v[96:97], s[94:95], 0, v[96:97]
	v_lshl_add_u64 v[98:99], s[6:7], 0, v[98:99]
	v_lshl_add_u64 v[96:97], v[96:97], 0, v[166:167]
	v_lshl_add_u64 v[98:99], v[98:99], 0, v[166:167]
	s_waitcnt vmcnt(1)
	v_lshlrev_b32_e32 v110, 16, v100
	v_and_b32_e32 v111, 0xffff0000, v100
	v_lshlrev_b32_e32 v100, 16, v101
	v_and_b32_e32 v101, 0xffff0000, v101
	v_lshlrev_b32_e32 v116, 16, v102
	v_and_b32_e32 v117, 0xffff0000, v102
	v_lshlrev_b32_e32 v102, 16, v103
	v_and_b32_e32 v103, 0xffff0000, v103
	v_mul_f32_e32 v118, 0xbfb8aa3b, v110
	v_mul_f32_e32 v119, 0xbfb8aa3b, v111
	v_mul_f32_e32 v124, 0xbfb8aa3b, v100
	v_mul_f32_e32 v125, 0xbfb8aa3b, v101
	v_mul_f32_e32 v126, 0xbfb8aa3b, v116
	v_mul_f32_e32 v127, 0xbfb8aa3b, v117
	v_mul_f32_e32 v136, 0xbfb8aa3b, v102
	v_mul_f32_e32 v137, 0xbfb8aa3b, v103
	v_exp_f32_e32 v118, v118
	v_exp_f32_e32 v119, v119
	v_exp_f32_e32 v124, v124
	v_exp_f32_e32 v125, v125
	v_exp_f32_e32 v126, v126
	v_exp_f32_e32 v127, v127
	v_exp_f32_e32 v136, v136
	v_exp_f32_e32 v137, v137
	v_add_f32_e32 v118, 1.0, v118
	v_add_f32_e32 v119, 1.0, v119
	v_add_f32_e32 v124, 1.0, v124
	v_add_f32_e32 v125, 1.0, v125
	v_add_f32_e32 v126, 1.0, v126
	v_add_f32_e32 v127, 1.0, v127
	v_add_f32_e32 v136, 1.0, v136
	v_add_f32_e32 v137, 1.0, v137
	v_rcp_f32_e32 v118, v118
	v_rcp_f32_e32 v119, v119
	v_rcp_f32_e32 v124, v124
	v_rcp_f32_e32 v125, v125
	v_rcp_f32_e32 v126, v126
	v_rcp_f32_e32 v127, v127
	v_rcp_f32_e32 v136, v136
	v_rcp_f32_e32 v137, v137
	v_pk_mul_f32 v[110:111], v[118:119], v[110:111]
	v_pk_mul_f32 v[100:101], v[124:125], v[100:101]
	v_pk_mul_f32 v[116:117], v[126:127], v[116:117]
	v_pk_mul_f32 v[102:103], v[136:137], v[102:103]
	v_pk_mul_f32 v[92:93], v[92:93], v[110:111]
	v_pk_mul_f32 v[94:95], v[94:95], v[100:101]
	v_pk_mul_f32 v[100:101], v[88:89], v[116:117]
	v_pk_mul_f32 v[102:103], v[90:91], v[102:103]
	v_cvt_pk_bf16_f32 v88, v92, v93
	v_cvt_pk_bf16_f32 v89, v94, v95
	v_cvt_pk_bf16_f32 v90, v100, v101
	v_cvt_pk_bf16_f32 v91, v102, v103
	global_load_dwordx4 v[92:95], v[98:99], off
	global_store_dwordx4 v[96:97], v[88:91], off
	s_nop 1
	v_add_u32_e32 v100, 0xa0, v168
	v_lshlrev_b64 v[88:89], 12, v[108:109]
	v_ashrrev_i32_e32 v101, 31, v100
	v_lshlrev_b64 v[90:91], 13, v[100:101]
	v_lshl_add_u64 v[88:89], s[94:95], 0, v[88:89]
	v_lshl_add_u64 v[90:91], s[6:7], 0, v[90:91]
	v_lshl_add_u64 v[88:89], v[88:89], 0, v[166:167]
	v_lshl_add_u64 v[90:91], v[90:91], 0, v[166:167]
	s_waitcnt vmcnt(1)
	v_lshlrev_b32_e32 v102, 16, v92
	v_and_b32_e32 v103, 0xffff0000, v92
	v_lshlrev_b32_e32 v92, 16, v93
	v_and_b32_e32 v93, 0xffff0000, v93
	v_lshlrev_b32_e32 v108, 16, v94
	v_and_b32_e32 v109, 0xffff0000, v94
	v_lshlrev_b32_e32 v94, 16, v95
	v_and_b32_e32 v95, 0xffff0000, v95
	v_mul_f32_e32 v110, 0xbfb8aa3b, v102
	v_mul_f32_e32 v111, 0xbfb8aa3b, v103
	v_mul_f32_e32 v116, 0xbfb8aa3b, v92
	v_mul_f32_e32 v117, 0xbfb8aa3b, v93
	v_mul_f32_e32 v118, 0xbfb8aa3b, v108
	v_mul_f32_e32 v119, 0xbfb8aa3b, v109
	v_mul_f32_e32 v124, 0xbfb8aa3b, v94
	v_mul_f32_e32 v125, 0xbfb8aa3b, v95
	v_exp_f32_e32 v110, v110
	v_exp_f32_e32 v111, v111
	v_exp_f32_e32 v116, v116
	v_exp_f32_e32 v117, v117
	v_exp_f32_e32 v118, v118
	v_exp_f32_e32 v119, v119
	v_exp_f32_e32 v124, v124
	v_exp_f32_e32 v125, v125
	v_add_f32_e32 v110, 1.0, v110
	v_add_f32_e32 v111, 1.0, v111
	v_add_f32_e32 v116, 1.0, v116
	v_add_f32_e32 v117, 1.0, v117
	v_add_f32_e32 v118, 1.0, v118
	v_add_f32_e32 v119, 1.0, v119
	v_add_f32_e32 v124, 1.0, v124
	v_add_f32_e32 v125, 1.0, v125
	v_rcp_f32_e32 v110, v110
	v_rcp_f32_e32 v111, v111
	v_rcp_f32_e32 v116, v116
	v_rcp_f32_e32 v117, v117
	v_rcp_f32_e32 v118, v118
	v_rcp_f32_e32 v119, v119
	v_rcp_f32_e32 v124, v124
	v_rcp_f32_e32 v125, v125
	v_pk_mul_f32 v[102:103], v[110:111], v[102:103]
	v_pk_mul_f32 v[92:93], v[116:117], v[92:93]
	v_pk_mul_f32 v[108:109], v[118:119], v[108:109]
	v_pk_mul_f32 v[94:95], v[124:125], v[94:95]
	v_pk_mul_f32 v[84:85], v[84:85], v[102:103]
	v_pk_mul_f32 v[86:87], v[86:87], v[92:93]
	v_pk_mul_f32 v[92:93], v[80:81], v[108:109]
	v_pk_mul_f32 v[94:95], v[82:83], v[94:95]
	v_cvt_pk_bf16_f32 v80, v84, v85
	v_cvt_pk_bf16_f32 v81, v86, v87
	v_cvt_pk_bf16_f32 v82, v92, v93
	v_cvt_pk_bf16_f32 v83, v94, v95
	global_load_dwordx4 v[84:87], v[90:91], off
	global_store_dwordx4 v[88:89], v[80:83], off
	s_nop 1
	v_add_u32_e32 v92, 0xb0, v168
	v_lshlrev_b64 v[80:81], 12, v[100:101]
	v_ashrrev_i32_e32 v93, 31, v92
	v_lshlrev_b64 v[82:83], 13, v[92:93]
	v_lshl_add_u64 v[80:81], s[94:95], 0, v[80:81]
	v_lshl_add_u64 v[82:83], s[6:7], 0, v[82:83]
	v_lshl_add_u64 v[80:81], v[80:81], 0, v[166:167]
	v_lshl_add_u64 v[82:83], v[82:83], 0, v[166:167]
	s_waitcnt vmcnt(1)
; __device__ __forceinline__ unsigned pk2(float lo, float hi) { f32x2 v = {lo, hi}; bf16x2_t b = __builtin_convertvector(v, bf16x2_t); return __builtin_bit_cast(unsigned, b); }
; __device__ __forceinline__ float silu_f(float z) { return z * __builtin_amdgcn_rcpf(1.0f + __expf(-z)); }
;     __device__ __forceinline__ void operator()(const f32x4 (&acc)[2][2][4][2], const Unit& u, int wr, int wc, int fr, int fq) const {
;     ...
;             const f32x4 s0 = *(const f32x4*)(ps + col0 + bj * HALF), s1 = *(const f32x4*)(ps + col0 + bj * HALF + 4);
; #pragma unroll
;             for (int ai = 0; ai < 2; ++ai)
; #pragma unroll
;                 for (int m = 0; m < 4; ++m) { const size_t r = (size_t)(row0 + ai * HALF + m * 16);
;                     const u32x4 zz = *(const u32x4*)(Z + r * ldz + col0 + bj * HALF);
;                     const f32x4 v0 = acc[ai][bj][m][0], v1 = acc[ai][bj][m][1];
;                     u32x4 w;
;                     w.x = pk2(v0[0] * s0[0] * silu_f(bflo(zz.x)), v0[1] * s0[1] * silu_f(bfhi(zz.x)));
;                     w.y = pk2(v0[2] * s0[2] * silu_f(bflo(zz.y)), v0[3] * s0[3] * silu_f(bfhi(zz.y)));
;                     w.z = pk2(v1[0] * s1[0] * silu_f(bflo(zz.z)), v1[1] * s1[1] * silu_f(bfhi(zz.z)));
;                     w.w = pk2(v1[2] * s1[2] * silu_f(bflo(zz.w)), v1[3] * s1[3] * silu_f(bfhi(zz.w)));
;                     *(u32x4*)(O + r * ldc + col0 + bj * HALF) = w; } }
	v_lshlrev_b32_e32 v94, 16, v84
	v_and_b32_e32 v95, 0xffff0000, v84
	v_lshlrev_b32_e32 v84, 16, v85
	v_and_b32_e32 v85, 0xffff0000, v85
	v_lshlrev_b32_e32 v100, 16, v86
	v_and_b32_e32 v101, 0xffff0000, v86
	v_lshlrev_b32_e32 v86, 16, v87
	v_and_b32_e32 v87, 0xffff0000, v87
	v_mul_f32_e32 v102, 0xbfb8aa3b, v94
	v_mul_f32_e32 v103, 0xbfb8aa3b, v95
	v_mul_f32_e32 v108, 0xbfb8aa3b, v84
	v_mul_f32_e32 v109, 0xbfb8aa3b, v85
	v_mul_f32_e32 v110, 0xbfb8aa3b, v100
	v_mul_f32_e32 v111, 0xbfb8aa3b, v101
	v_mul_f32_e32 v116, 0xbfb8aa3b, v86
	v_mul_f32_e32 v117, 0xbfb8aa3b, v87
	v_exp_f32_e32 v102, v102
	v_exp_f32_e32 v103, v103
	v_exp_f32_e32 v108, v108
	v_exp_f32_e32 v109, v109
	v_exp_f32_e32 v110, v110
	v_exp_f32_e32 v111, v111
	v_exp_f32_e32 v116, v116
	v_exp_f32_e32 v117, v117
	v_add_f32_e32 v102, 1.0, v102
	v_add_f32_e32 v103, 1.0, v103
	v_add_f32_e32 v108, 1.0, v108
	v_add_f32_e32 v109, 1.0, v109
	v_add_f32_e32 v110, 1.0, v110
	v_add_f32_e32 v111, 1.0, v111
	v_add_f32_e32 v116, 1.0, v116
	v_add_f32_e32 v117, 1.0, v117
	v_rcp_f32_e32 v102, v102
	v_rcp_f32_e32 v103, v103
	v_rcp_f32_e32 v108, v108
	v_rcp_f32_e32 v109, v109
	v_rcp_f32_e32 v110, v110
	v_rcp_f32_e32 v111, v111
	v_rcp_f32_e32 v116, v116
	v_rcp_f32_e32 v117, v117
	v_pk_mul_f32 v[94:95], v[102:103], v[94:95]
	v_pk_mul_f32 v[84:85], v[108:109], v[84:85]
	v_pk_mul_f32 v[100:101], v[110:111], v[100:101]
	v_pk_mul_f32 v[86:87], v[116:117], v[86:87]
	v_pk_mul_f32 v[76:77], v[76:77], v[94:95]
	v_pk_mul_f32 v[78:79], v[78:79], v[84:85]
	v_pk_mul_f32 v[84:85], v[72:73], v[100:101]
	v_pk_mul_f32 v[86:87], v[74:75], v[86:87]
	v_cvt_pk_bf16_f32 v72, v76, v77
	v_cvt_pk_bf16_f32 v73, v78, v79
	v_cvt_pk_bf16_f32 v74, v84, v85
	v_cvt_pk_bf16_f32 v75, v86, v87
	global_store_dwordx4 v[80:81], v[72:75], off
	global_load_dwordx4 v[74:77], v[82:83], off
	s_waitcnt vmcnt(0)
	v_lshlrev_b32_e32 v78, 16, v74
	v_and_b32_e32 v79, 0xffff0000, v74
	v_lshlrev_b32_e32 v74, 16, v75
	v_and_b32_e32 v75, 0xffff0000, v75
	v_lshlrev_b32_e32 v84, 16, v76
	v_and_b32_e32 v85, 0xffff0000, v76
	v_lshlrev_b32_e32 v76, 16, v77
	v_and_b32_e32 v77, 0xffff0000, v77
	v_lshlrev_b64 v[72:73], 12, v[92:93]
	v_mul_f32_e32 v86, 0xbfb8aa3b, v78
	v_mul_f32_e32 v87, 0xbfb8aa3b, v79
	v_mul_f32_e32 v92, 0xbfb8aa3b, v74
	v_mul_f32_e32 v93, 0xbfb8aa3b, v75
	v_mul_f32_e32 v94, 0xbfb8aa3b, v84
	v_mul_f32_e32 v95, 0xbfb8aa3b, v85
	v_mul_f32_e32 v100, 0xbfb8aa3b, v76
	v_mul_f32_e32 v101, 0xbfb8aa3b, v77
	v_exp_f32_e32 v86, v86
	v_exp_f32_e32 v87, v87
	v_exp_f32_e32 v92, v92
	v_exp_f32_e32 v93, v93
	v_exp_f32_e32 v94, v94
	v_exp_f32_e32 v95, v95
	v_exp_f32_e32 v100, v100
	v_exp_f32_e32 v101, v101
	v_add_f32_e32 v86, 1.0, v86
	v_add_f32_e32 v87, 1.0, v87
	v_add_f32_e32 v92, 1.0, v92
	v_add_f32_e32 v93, 1.0, v93
	v_add_f32_e32 v94, 1.0, v94
	v_add_f32_e32 v95, 1.0, v95
	v_add_f32_e32 v100, 1.0, v100
	v_add_f32_e32 v101, 1.0, v101
	v_rcp_f32_e32 v86, v86
	v_rcp_f32_e32 v87, v87
	v_rcp_f32_e32 v92, v92
	v_rcp_f32_e32 v93, v93
	v_rcp_f32_e32 v94, v94
	v_rcp_f32_e32 v95, v95
	v_rcp_f32_e32 v100, v100
	v_rcp_f32_e32 v101, v101
	v_pk_mul_f32 v[78:79], v[86:87], v[78:79]
	v_pk_mul_f32 v[74:75], v[92:93], v[74:75]
	v_pk_mul_f32 v[84:85], v[94:95], v[84:85]
	v_pk_mul_f32 v[76:77], v[100:101], v[76:77]
	v_lshl_add_u64 v[72:73], s[94:95], 0, v[72:73]
	v_pk_mul_f32 v[68:69], v[68:69], v[78:79]
	v_pk_mul_f32 v[70:71], v[70:71], v[74:75]
	v_pk_mul_f32 v[74:75], v[64:65], v[84:85]
	v_pk_mul_f32 v[76:77], v[66:67], v[76:77]
	v_lshl_add_u64 v[72:73], v[72:73], 0, v[166:167]
	v_cvt_pk_bf16_f32 v64, v68, v69
	v_cvt_pk_bf16_f32 v65, v70, v71
	v_cvt_pk_bf16_f32 v66, v74, v75
	v_cvt_pk_bf16_f32 v67, v76, v77
	global_store_dwordx4 v[72:73], v[64:67], off
	global_load_dwordx4 v[68:71], v[164:165], off offset:512
	s_nop 0
	global_load_dwordx4 v[64:67], v[164:165], off offset:528
	v_lshlrev_b32_e32 v74, 16, v140
	v_and_b32_e32 v75, 0xffff0000, v140
	v_lshlrev_b32_e32 v76, 16, v141
	v_and_b32_e32 v77, 0xffff0000, v141
	v_lshlrev_b32_e32 v78, 16, v142
	v_and_b32_e32 v79, 0xffff0000, v142
	v_lshlrev_b32_e32 v84, 16, v143
	v_and_b32_e32 v85, 0xffff0000, v143
	v_mul_f32_e32 v86, 0xbfb8aa3b, v74
	v_mul_f32_e32 v87, 0xbfb8aa3b, v75
	v_mul_f32_e32 v92, 0xbfb8aa3b, v76
	v_mul_f32_e32 v93, 0xbfb8aa3b, v77
	v_mul_f32_e32 v94, 0xbfb8aa3b, v78
	v_mul_f32_e32 v95, 0xbfb8aa3b, v79
	v_mul_f32_e32 v100, 0xbfb8aa3b, v84
	v_mul_f32_e32 v101, 0xbfb8aa3b, v85
	v_exp_f32_e32 v86, v86
	v_exp_f32_e32 v87, v87
	v_exp_f32_e32 v92, v92
	v_exp_f32_e32 v93, v93
	v_exp_f32_e32 v94, v94
	v_exp_f32_e32 v95, v95
	v_exp_f32_e32 v100, v100
	v_exp_f32_e32 v101, v101
	v_add_f32_e32 v86, 1.0, v86
	v_add_f32_e32 v87, 1.0, v87
	v_add_f32_e32 v92, 1.0, v92
	v_add_f32_e32 v93, 1.0, v93
	v_add_f32_e32 v94, 1.0, v94
	v_add_f32_e32 v95, 1.0, v95
	v_add_f32_e32 v100, 1.0, v100
	v_add_f32_e32 v101, 1.0, v101
	v_rcp_f32_e32 v86, v86
	v_rcp_f32_e32 v87, v87
	v_rcp_f32_e32 v92, v92
	v_rcp_f32_e32 v93, v93
	v_rcp_f32_e32 v94, v94
	v_rcp_f32_e32 v95, v95
	v_rcp_f32_e32 v100, v100
	v_rcp_f32_e32 v101, v101
	v_pk_mul_f32 v[74:75], v[86:87], v[74:75]
	v_pk_mul_f32 v[76:77], v[92:93], v[76:77]
	v_pk_mul_f32 v[78:79], v[94:95], v[78:79]
	v_pk_mul_f32 v[84:85], v[100:101], v[84:85]
	s_waitcnt vmcnt(1)
	v_pk_mul_f32 v[62:63], v[62:63], v[70:71]
	v_pk_mul_f32 v[60:61], v[60:61], v[68:69]
	s_waitcnt vmcnt(0)
; __device__ __forceinline__ unsigned pk2(float lo, float hi) { f32x2 v = {lo, hi}; bf16x2_t b = __builtin_convertvector(v, bf16x2_t); return __builtin_bit_cast(unsigned, b); }
; __device__ __forceinline__ float silu_f(float z) { return z * __builtin_amdgcn_rcpf(1.0f + __expf(-z)); }
;     __device__ __forceinline__ void operator()(const f32x4 (&acc)[2][2][4][2], const Unit& u, int wr, int wc, int fr, int fq) const {
;     ...
;                 for (int m = 0; m < 4; ++m) { const size_t r = (size_t)(row0 + ai * HALF + m * 16);
;                     const u32x4 zz = *(const u32x4*)(Z + r * ldz + col0 + bj * HALF);
;                     const f32x4 v0 = acc[ai][bj][m][0], v1 = acc[ai][bj][m][1];
;                     u32x4 w;
;                     w.x = pk2(v0[0] * s0[0] * silu_f(bflo(zz.x)), v0[1] * s0[1] * silu_f(bfhi(zz.x)));
;                     w.y = pk2(v0[2] * s0[2] * silu_f(bflo(zz.y)), v0[3] * s0[3] * silu_f(bfhi(zz.y)));
;                     w.z = pk2(v1[0] * s1[0] * silu_f(bflo(zz.z)), v1[1] * s1[1] * silu_f(bfhi(zz.z)));
;                     w.w = pk2(v1[2] * s1[2] * silu_f(bflo(zz.w)), v1[3] * s1[3] * silu_f(bfhi(zz.w)));
;                     *(u32x4*)(O + r * ldc + col0 + bj * HALF) = w; } }
	v_pk_mul_f32 v[58:59], v[58:59], v[66:67]
	v_pk_mul_f32 v[56:57], v[56:57], v[64:65]
	v_pk_mul_f32 v[60:61], v[60:61], v[74:75]
	v_pk_mul_f32 v[62:63], v[62:63], v[76:77]
	v_pk_mul_f32 v[74:75], v[56:57], v[78:79]
	v_pk_mul_f32 v[76:77], v[58:59], v[84:85]
	v_cvt_pk_bf16_f32 v56, v60, v61
	v_cvt_pk_bf16_f32 v57, v62, v63
	v_cvt_pk_bf16_f32 v58, v74, v75
	v_cvt_pk_bf16_f32 v59, v76, v77
	global_store_dwordx4 v[160:161], v[56:59], off offset:256
	global_load_dwordx4 v[56:59], v[162:163], off offset:256
	v_pk_mul_f32 v[54:55], v[54:55], v[70:71]
	v_pk_mul_f32 v[52:53], v[52:53], v[68:69]
	v_pk_mul_f32 v[50:51], v[50:51], v[66:67]
	v_pk_mul_f32 v[48:49], v[48:49], v[64:65]
	v_pk_mul_f32 v[46:47], v[46:47], v[70:71]
	v_pk_mul_f32 v[44:45], v[44:45], v[68:69]
	v_pk_mul_f32 v[42:43], v[42:43], v[66:67]
	v_pk_mul_f32 v[40:41], v[40:41], v[64:65]
	v_pk_mul_f32 v[38:39], v[38:39], v[70:71]
	v_pk_mul_f32 v[36:37], v[36:37], v[68:69]
	v_pk_mul_f32 v[34:35], v[34:35], v[66:67]
	v_pk_mul_f32 v[32:33], v[32:33], v[64:65]
	v_pk_mul_f32 v[30:31], v[30:31], v[70:71]
	v_pk_mul_f32 v[28:29], v[28:29], v[68:69]
	v_pk_mul_f32 v[26:27], v[26:27], v[66:67]
	v_pk_mul_f32 v[24:25], v[24:25], v[64:65]
	v_pk_mul_f32 v[22:23], v[22:23], v[70:71]
	v_pk_mul_f32 v[20:21], v[20:21], v[68:69]
	v_pk_mul_f32 v[18:19], v[18:19], v[66:67]
	v_pk_mul_f32 v[16:17], v[16:17], v[64:65]
	v_pk_mul_f32 v[14:15], v[14:15], v[70:71]
	v_pk_mul_f32 v[12:13], v[12:13], v[68:69]
	v_pk_mul_f32 v[10:11], v[10:11], v[66:67]
	v_pk_mul_f32 v[8:9], v[8:9], v[64:65]
	v_pk_mul_f32 v[6:7], v[6:7], v[70:71]
	v_pk_mul_f32 v[4:5], v[4:5], v[68:69]
	v_pk_mul_f32 v[2:3], v[2:3], v[66:67]
	v_pk_mul_f32 v[0:1], v[0:1], v[64:65]
	s_waitcnt vmcnt(0)
	v_lshlrev_b32_e32 v60, 16, v56
	v_and_b32_e32 v61, 0xffff0000, v56
	v_lshlrev_b32_e32 v56, 16, v57
	v_and_b32_e32 v57, 0xffff0000, v57
	v_lshlrev_b32_e32 v62, 16, v58
	v_and_b32_e32 v63, 0xffff0000, v58
	v_lshlrev_b32_e32 v58, 16, v59
	v_and_b32_e32 v59, 0xffff0000, v59
	v_mul_f32_e32 v74, 0xbfb8aa3b, v60
	v_mul_f32_e32 v75, 0xbfb8aa3b, v61
	v_mul_f32_e32 v76, 0xbfb8aa3b, v56
	v_mul_f32_e32 v77, 0xbfb8aa3b, v57
	v_mul_f32_e32 v78, 0xbfb8aa3b, v62
	v_mul_f32_e32 v79, 0xbfb8aa3b, v63
	v_mul_f32_e32 v84, 0xbfb8aa3b, v58
	v_mul_f32_e32 v85, 0xbfb8aa3b, v59
	v_exp_f32_e32 v74, v74
	v_exp_f32_e32 v75, v75
	v_exp_f32_e32 v76, v76
	v_exp_f32_e32 v77, v77
	v_exp_f32_e32 v78, v78
	v_exp_f32_e32 v79, v79
	v_exp_f32_e32 v84, v84
	v_exp_f32_e32 v85, v85
	v_add_f32_e32 v74, 1.0, v74
	v_add_f32_e32 v75, 1.0, v75
	v_add_f32_e32 v76, 1.0, v76
	v_add_f32_e32 v77, 1.0, v77
	v_add_f32_e32 v78, 1.0, v78
	v_add_f32_e32 v79, 1.0, v79
	v_add_f32_e32 v84, 1.0, v84
	v_add_f32_e32 v85, 1.0, v85
	v_rcp_f32_e32 v74, v74
	v_rcp_f32_e32 v75, v75
	v_rcp_f32_e32 v76, v76
	v_rcp_f32_e32 v77, v77
	v_rcp_f32_e32 v78, v78
	v_rcp_f32_e32 v79, v79
	v_rcp_f32_e32 v84, v84
	v_rcp_f32_e32 v85, v85
	v_pk_mul_f32 v[60:61], v[74:75], v[60:61]
	v_pk_mul_f32 v[56:57], v[76:77], v[56:57]
	v_pk_mul_f32 v[62:63], v[78:79], v[62:63]
	v_pk_mul_f32 v[58:59], v[84:85], v[58:59]
	v_pk_mul_f32 v[52:53], v[52:53], v[60:61]
	v_pk_mul_f32 v[54:55], v[54:55], v[56:57]
	v_pk_mul_f32 v[56:57], v[48:49], v[62:63]
	v_pk_mul_f32 v[58:59], v[50:51], v[58:59]
	v_cvt_pk_bf16_f32 v48, v52, v53
	v_cvt_pk_bf16_f32 v49, v54, v55
	v_cvt_pk_bf16_f32 v50, v56, v57
	v_cvt_pk_bf16_f32 v51, v58, v59
	global_store_dwordx4 v[120:121], v[48:51], off offset:256
	global_load_dwordx4 v[48:51], v[122:123], off offset:256
	s_waitcnt vmcnt(0)
	v_lshlrev_b32_e32 v52, 16, v48
	v_and_b32_e32 v53, 0xffff0000, v48
	v_lshlrev_b32_e32 v48, 16, v49
	v_and_b32_e32 v49, 0xffff0000, v49
	v_lshlrev_b32_e32 v54, 16, v50
	v_and_b32_e32 v55, 0xffff0000, v50
	v_lshlrev_b32_e32 v50, 16, v51
	v_and_b32_e32 v51, 0xffff0000, v51
	v_mul_f32_e32 v56, 0xbfb8aa3b, v52
	v_mul_f32_e32 v57, 0xbfb8aa3b, v53
	v_mul_f32_e32 v58, 0xbfb8aa3b, v48
	v_mul_f32_e32 v59, 0xbfb8aa3b, v49
	v_mul_f32_e32 v60, 0xbfb8aa3b, v54
	v_mul_f32_e32 v61, 0xbfb8aa3b, v55
	v_mul_f32_e32 v62, 0xbfb8aa3b, v50
	v_mul_f32_e32 v63, 0xbfb8aa3b, v51
	v_exp_f32_e32 v56, v56
	v_exp_f32_e32 v57, v57
	v_exp_f32_e32 v58, v58
	v_exp_f32_e32 v59, v59
	v_exp_f32_e32 v60, v60
	v_exp_f32_e32 v61, v61
	v_exp_f32_e32 v62, v62
	v_exp_f32_e32 v63, v63
	v_add_f32_e32 v56, 1.0, v56
	v_add_f32_e32 v57, 1.0, v57
	v_add_f32_e32 v58, 1.0, v58
	v_add_f32_e32 v59, 1.0, v59
	v_add_f32_e32 v60, 1.0, v60
	v_add_f32_e32 v61, 1.0, v61
	v_add_f32_e32 v62, 1.0, v62
	v_add_f32_e32 v63, 1.0, v63
	v_rcp_f32_e32 v56, v56
	v_rcp_f32_e32 v57, v57
	v_rcp_f32_e32 v58, v58
	v_rcp_f32_e32 v59, v59
	v_rcp_f32_e32 v60, v60
	v_rcp_f32_e32 v61, v61
	v_rcp_f32_e32 v62, v62
	v_rcp_f32_e32 v63, v63
	v_pk_mul_f32 v[52:53], v[56:57], v[52:53]
	v_pk_mul_f32 v[48:49], v[58:59], v[48:49]
	v_pk_mul_f32 v[54:55], v[60:61], v[54:55]
	v_pk_mul_f32 v[50:51], v[62:63], v[50:51]
	v_pk_mul_f32 v[44:45], v[44:45], v[52:53]
	v_pk_mul_f32 v[46:47], v[46:47], v[48:49]
	v_pk_mul_f32 v[48:49], v[40:41], v[54:55]
	v_pk_mul_f32 v[50:51], v[42:43], v[50:51]
	v_cvt_pk_bf16_f32 v40, v44, v45
	v_cvt_pk_bf16_f32 v41, v46, v47
	v_cvt_pk_bf16_f32 v42, v48, v49
	v_cvt_pk_bf16_f32 v43, v50, v51
	global_store_dwordx4 v[112:113], v[40:43], off offset:256
	global_load_dwordx4 v[40:43], v[114:115], off offset:256
	s_waitcnt vmcnt(0)
; __device__ __forceinline__ unsigned pk2(float lo, float hi) { f32x2 v = {lo, hi}; bf16x2_t b = __builtin_convertvector(v, bf16x2_t); return __builtin_bit_cast(unsigned, b); }
; __device__ __forceinline__ float silu_f(float z) { return z * __builtin_amdgcn_rcpf(1.0f + __expf(-z)); }
;     __device__ __forceinline__ void operator()(const f32x4 (&acc)[2][2][4][2], const Unit& u, int wr, int wc, int fr, int fq) const {
;     ...
;                 for (int m = 0; m < 4; ++m) { const size_t r = (size_t)(row0 + ai * HALF + m * 16);
;                     const u32x4 zz = *(const u32x4*)(Z + r * ldz + col0 + bj * HALF);
;                     const f32x4 v0 = acc[ai][bj][m][0], v1 = acc[ai][bj][m][1];
;                     u32x4 w;
;                     w.x = pk2(v0[0] * s0[0] * silu_f(bflo(zz.x)), v0[1] * s0[1] * silu_f(bfhi(zz.x)));
;                     w.y = pk2(v0[2] * s0[2] * silu_f(bflo(zz.y)), v0[3] * s0[3] * silu_f(bfhi(zz.y)));
;                     w.z = pk2(v1[0] * s1[0] * silu_f(bflo(zz.z)), v1[1] * s1[1] * silu_f(bfhi(zz.z)));
;                     w.w = pk2(v1[2] * s1[2] * silu_f(bflo(zz.w)), v1[3] * s1[3] * silu_f(bfhi(zz.w)));
;                     *(u32x4*)(O + r * ldc + col0 + bj * HALF) = w; } }
	v_lshlrev_b32_e32 v44, 16, v40
	v_and_b32_e32 v45, 0xffff0000, v40
	v_lshlrev_b32_e32 v40, 16, v41
	v_and_b32_e32 v41, 0xffff0000, v41
	v_lshlrev_b32_e32 v46, 16, v42
	v_and_b32_e32 v47, 0xffff0000, v42
	v_lshlrev_b32_e32 v42, 16, v43
	v_and_b32_e32 v43, 0xffff0000, v43
	v_mul_f32_e32 v48, 0xbfb8aa3b, v44
	v_mul_f32_e32 v49, 0xbfb8aa3b, v45
	v_mul_f32_e32 v50, 0xbfb8aa3b, v40
	v_mul_f32_e32 v51, 0xbfb8aa3b, v41
	v_mul_f32_e32 v52, 0xbfb8aa3b, v46
	v_mul_f32_e32 v53, 0xbfb8aa3b, v47
	v_mul_f32_e32 v54, 0xbfb8aa3b, v42
	v_mul_f32_e32 v55, 0xbfb8aa3b, v43
	v_exp_f32_e32 v48, v48
	v_exp_f32_e32 v49, v49
	v_exp_f32_e32 v50, v50
	v_exp_f32_e32 v51, v51
	v_exp_f32_e32 v52, v52
	v_exp_f32_e32 v53, v53
	v_exp_f32_e32 v54, v54
	v_exp_f32_e32 v55, v55
	v_add_f32_e32 v48, 1.0, v48
	v_add_f32_e32 v49, 1.0, v49
	v_add_f32_e32 v50, 1.0, v50
	v_add_f32_e32 v51, 1.0, v51
	v_add_f32_e32 v52, 1.0, v52
	v_add_f32_e32 v53, 1.0, v53
	v_add_f32_e32 v54, 1.0, v54
	v_add_f32_e32 v55, 1.0, v55
	v_rcp_f32_e32 v48, v48
	v_rcp_f32_e32 v49, v49
	v_rcp_f32_e32 v50, v50
	v_rcp_f32_e32 v51, v51
	v_rcp_f32_e32 v52, v52
	v_rcp_f32_e32 v53, v53
	v_rcp_f32_e32 v54, v54
	v_rcp_f32_e32 v55, v55
	v_pk_mul_f32 v[44:45], v[48:49], v[44:45]
	v_pk_mul_f32 v[40:41], v[50:51], v[40:41]
	v_pk_mul_f32 v[46:47], v[52:53], v[46:47]
	v_pk_mul_f32 v[42:43], v[54:55], v[42:43]
	v_pk_mul_f32 v[36:37], v[36:37], v[44:45]
	v_pk_mul_f32 v[38:39], v[38:39], v[40:41]
	v_pk_mul_f32 v[40:41], v[32:33], v[46:47]
	v_pk_mul_f32 v[42:43], v[34:35], v[42:43]
	v_cvt_pk_bf16_f32 v32, v36, v37
	v_cvt_pk_bf16_f32 v33, v38, v39
	v_cvt_pk_bf16_f32 v34, v40, v41
	v_cvt_pk_bf16_f32 v35, v42, v43
	global_store_dwordx4 v[104:105], v[32:35], off offset:256
	global_load_dwordx4 v[32:35], v[106:107], off offset:256
	s_waitcnt vmcnt(0)
	v_lshlrev_b32_e32 v36, 16, v32
	v_and_b32_e32 v37, 0xffff0000, v32
	v_lshlrev_b32_e32 v32, 16, v33
	v_and_b32_e32 v33, 0xffff0000, v33
	v_lshlrev_b32_e32 v38, 16, v34
	v_and_b32_e32 v39, 0xffff0000, v34
	v_lshlrev_b32_e32 v34, 16, v35
	v_and_b32_e32 v35, 0xffff0000, v35
	v_mul_f32_e32 v40, 0xbfb8aa3b, v36
	v_mul_f32_e32 v41, 0xbfb8aa3b, v37
	v_mul_f32_e32 v42, 0xbfb8aa3b, v32
	v_mul_f32_e32 v43, 0xbfb8aa3b, v33
	v_mul_f32_e32 v44, 0xbfb8aa3b, v38
	v_mul_f32_e32 v45, 0xbfb8aa3b, v39
	v_mul_f32_e32 v46, 0xbfb8aa3b, v34
	v_mul_f32_e32 v47, 0xbfb8aa3b, v35
	v_exp_f32_e32 v40, v40
	v_exp_f32_e32 v41, v41
	v_exp_f32_e32 v42, v42
	v_exp_f32_e32 v43, v43
	v_exp_f32_e32 v44, v44
	v_exp_f32_e32 v45, v45
	v_exp_f32_e32 v46, v46
	v_exp_f32_e32 v47, v47
	v_add_f32_e32 v40, 1.0, v40
	v_add_f32_e32 v41, 1.0, v41
	v_add_f32_e32 v42, 1.0, v42
	v_add_f32_e32 v43, 1.0, v43
	v_add_f32_e32 v44, 1.0, v44
	v_add_f32_e32 v45, 1.0, v45
	v_add_f32_e32 v46, 1.0, v46
	v_add_f32_e32 v47, 1.0, v47
	v_rcp_f32_e32 v40, v40
	v_rcp_f32_e32 v41, v41
	v_rcp_f32_e32 v42, v42
	v_rcp_f32_e32 v43, v43
	v_rcp_f32_e32 v44, v44
	v_rcp_f32_e32 v45, v45
	v_rcp_f32_e32 v46, v46
	v_rcp_f32_e32 v47, v47
	v_pk_mul_f32 v[36:37], v[40:41], v[36:37]
	v_pk_mul_f32 v[32:33], v[42:43], v[32:33]
	v_pk_mul_f32 v[38:39], v[44:45], v[38:39]
	v_pk_mul_f32 v[34:35], v[46:47], v[34:35]
	v_pk_mul_f32 v[28:29], v[28:29], v[36:37]
	v_pk_mul_f32 v[30:31], v[30:31], v[32:33]
	v_pk_mul_f32 v[32:33], v[24:25], v[38:39]
	v_pk_mul_f32 v[34:35], v[26:27], v[34:35]
	v_cvt_pk_bf16_f32 v24, v28, v29
	v_cvt_pk_bf16_f32 v25, v30, v31
	v_cvt_pk_bf16_f32 v26, v32, v33
	v_cvt_pk_bf16_f32 v27, v34, v35
	global_store_dwordx4 v[96:97], v[24:27], off offset:256
	global_load_dwordx4 v[24:27], v[98:99], off offset:256
	s_waitcnt vmcnt(0)
; __device__ __forceinline__ unsigned pk2(float lo, float hi) { f32x2 v = {lo, hi}; bf16x2_t b = __builtin_convertvector(v, bf16x2_t); return __builtin_bit_cast(unsigned, b); }
; __device__ __forceinline__ float silu_f(float z) { return z * __builtin_amdgcn_rcpf(1.0f + __expf(-z)); }
; #define PG8_BAR __builtin_amdgcn_s_barrier()
;     __device__ __forceinline__ void operator()(const f32x4 (&acc)[2][2][4][2], const Unit& u, int wr, int wc, int fr, int fq) const {
;     ...
;                 for (int m = 0; m < 4; ++m) { const size_t r = (size_t)(row0 + ai * HALF + m * 16);
;                     const u32x4 zz = *(const u32x4*)(Z + r * ldz + col0 + bj * HALF);
;                     const f32x4 v0 = acc[ai][bj][m][0], v1 = acc[ai][bj][m][1];
;                     u32x4 w;
;                     w.x = pk2(v0[0] * s0[0] * silu_f(bflo(zz.x)), v0[1] * s0[1] * silu_f(bfhi(zz.x)));
;                     w.y = pk2(v0[2] * s0[2] * silu_f(bflo(zz.y)), v0[3] * s0[3] * silu_f(bfhi(zz.y)));
;                     w.z = pk2(v1[0] * s1[0] * silu_f(bflo(zz.z)), v1[1] * s1[1] * silu_f(bfhi(zz.z)));
;                     w.w = pk2(v1[2] * s1[2] * silu_f(bflo(zz.w)), v1[3] * s1[3] * silu_f(bfhi(zz.w)));
;                     *(u32x4*)(O + r * ldc + col0 + bj * HALF) = w; } }
; template <class Epi, class Sched>
; __device__ __forceinline__ void gemm_phase(LAS unsigned char* lds, const Gemm g, const Sched& S, const Epi& E, const int tid) {
;     ...
;         if (!has_next) break;
; #pragma unroll
;         for (int a = 0; a < 2; ++a)
; #pragma unroll
;             for (int b = 0; b < 2; ++b)
; #pragma unroll
;                 for (int m = 0; m < 4; ++m)
; #pragma unroll
;                     for (int n = 0; n < 2; ++n) acc[a][b][m][n] = (f32x4){0.f, 0.f, 0.f, 0.f};
;         cur = nxt; cA = nA; cB = nB; ++ui;
;         if (wr == 1) PG8_BAR;
	v_lshlrev_b32_e32 v28, 16, v24
	v_and_b32_e32 v29, 0xffff0000, v24
	v_lshlrev_b32_e32 v24, 16, v25
	v_and_b32_e32 v25, 0xffff0000, v25
	v_lshlrev_b32_e32 v30, 16, v26
	v_and_b32_e32 v31, 0xffff0000, v26
	v_lshlrev_b32_e32 v26, 16, v27
	v_and_b32_e32 v27, 0xffff0000, v27
	v_mul_f32_e32 v32, 0xbfb8aa3b, v28
	v_mul_f32_e32 v33, 0xbfb8aa3b, v29
	v_mul_f32_e32 v34, 0xbfb8aa3b, v24
	v_mul_f32_e32 v35, 0xbfb8aa3b, v25
	v_mul_f32_e32 v36, 0xbfb8aa3b, v30
	v_mul_f32_e32 v37, 0xbfb8aa3b, v31
	v_mul_f32_e32 v38, 0xbfb8aa3b, v26
	v_mul_f32_e32 v39, 0xbfb8aa3b, v27
	v_exp_f32_e32 v32, v32
	v_exp_f32_e32 v33, v33
	v_exp_f32_e32 v34, v34
	v_exp_f32_e32 v35, v35
	v_exp_f32_e32 v36, v36
	v_exp_f32_e32 v37, v37
	v_exp_f32_e32 v38, v38
	v_exp_f32_e32 v39, v39
	v_add_f32_e32 v32, 1.0, v32
	v_add_f32_e32 v33, 1.0, v33
	v_add_f32_e32 v34, 1.0, v34
	v_add_f32_e32 v35, 1.0, v35
	v_add_f32_e32 v36, 1.0, v36
	v_add_f32_e32 v37, 1.0, v37
	v_add_f32_e32 v38, 1.0, v38
	v_add_f32_e32 v39, 1.0, v39
	v_rcp_f32_e32 v32, v32
	v_rcp_f32_e32 v33, v33
	v_rcp_f32_e32 v34, v34
	v_rcp_f32_e32 v35, v35
	v_rcp_f32_e32 v36, v36
	v_rcp_f32_e32 v37, v37
	v_rcp_f32_e32 v38, v38
	v_rcp_f32_e32 v39, v39
	v_pk_mul_f32 v[28:29], v[32:33], v[28:29]
	v_pk_mul_f32 v[24:25], v[34:35], v[24:25]
	v_pk_mul_f32 v[30:31], v[36:37], v[30:31]
	v_pk_mul_f32 v[26:27], v[38:39], v[26:27]
	v_pk_mul_f32 v[20:21], v[20:21], v[28:29]
	v_pk_mul_f32 v[22:23], v[22:23], v[24:25]
	v_pk_mul_f32 v[24:25], v[16:17], v[30:31]
	v_pk_mul_f32 v[26:27], v[18:19], v[26:27]
	v_cvt_pk_bf16_f32 v16, v20, v21
	v_cvt_pk_bf16_f32 v17, v22, v23
	v_cvt_pk_bf16_f32 v18, v24, v25
	v_cvt_pk_bf16_f32 v19, v26, v27
	global_store_dwordx4 v[88:89], v[16:19], off offset:256
	global_load_dwordx4 v[16:19], v[90:91], off offset:256
	s_waitcnt vmcnt(0)
	v_lshlrev_b32_e32 v20, 16, v16
	v_and_b32_e32 v21, 0xffff0000, v16
	v_lshlrev_b32_e32 v16, 16, v17
	v_and_b32_e32 v17, 0xffff0000, v17
	v_lshlrev_b32_e32 v22, 16, v18
	v_and_b32_e32 v23, 0xffff0000, v18
	v_lshlrev_b32_e32 v18, 16, v19
	v_and_b32_e32 v19, 0xffff0000, v19
	v_mul_f32_e32 v24, 0xbfb8aa3b, v20
	v_mul_f32_e32 v25, 0xbfb8aa3b, v21
	v_mul_f32_e32 v26, 0xbfb8aa3b, v16
	v_mul_f32_e32 v27, 0xbfb8aa3b, v17
	v_mul_f32_e32 v28, 0xbfb8aa3b, v22
	v_mul_f32_e32 v29, 0xbfb8aa3b, v23
	v_mul_f32_e32 v30, 0xbfb8aa3b, v18
	v_mul_f32_e32 v31, 0xbfb8aa3b, v19
	v_exp_f32_e32 v24, v24
	v_exp_f32_e32 v25, v25
	v_exp_f32_e32 v26, v26
	v_exp_f32_e32 v27, v27
	v_exp_f32_e32 v28, v28
	v_exp_f32_e32 v29, v29
	v_exp_f32_e32 v30, v30
	v_exp_f32_e32 v31, v31
	v_add_f32_e32 v24, 1.0, v24
	v_add_f32_e32 v25, 1.0, v25
	v_add_f32_e32 v26, 1.0, v26
	v_add_f32_e32 v27, 1.0, v27
	v_add_f32_e32 v28, 1.0, v28
	v_add_f32_e32 v29, 1.0, v29
	v_add_f32_e32 v30, 1.0, v30
	v_add_f32_e32 v31, 1.0, v31
	v_rcp_f32_e32 v24, v24
	v_rcp_f32_e32 v25, v25
	v_rcp_f32_e32 v26, v26
	v_rcp_f32_e32 v27, v27
	v_rcp_f32_e32 v28, v28
	v_rcp_f32_e32 v29, v29
	v_rcp_f32_e32 v30, v30
	v_rcp_f32_e32 v31, v31
	v_pk_mul_f32 v[20:21], v[24:25], v[20:21]
	v_pk_mul_f32 v[16:17], v[26:27], v[16:17]
	v_pk_mul_f32 v[22:23], v[28:29], v[22:23]
	v_pk_mul_f32 v[18:19], v[30:31], v[18:19]
	v_pk_mul_f32 v[12:13], v[12:13], v[20:21]
	v_pk_mul_f32 v[14:15], v[14:15], v[16:17]
	v_pk_mul_f32 v[16:17], v[8:9], v[22:23]
	v_pk_mul_f32 v[18:19], v[10:11], v[18:19]
	v_cvt_pk_bf16_f32 v8, v12, v13
	v_cvt_pk_bf16_f32 v9, v14, v15
	v_cvt_pk_bf16_f32 v10, v16, v17
	v_cvt_pk_bf16_f32 v11, v18, v19
	global_store_dwordx4 v[80:81], v[8:11], off offset:256
	global_load_dwordx4 v[8:11], v[82:83], off offset:256
	s_waitcnt vmcnt(0)
	v_lshlrev_b32_e32 v12, 16, v8
	v_and_b32_e32 v13, 0xffff0000, v8
	v_lshlrev_b32_e32 v8, 16, v9
	v_and_b32_e32 v9, 0xffff0000, v9
	v_lshlrev_b32_e32 v14, 16, v10
	v_and_b32_e32 v15, 0xffff0000, v10
	v_lshlrev_b32_e32 v10, 16, v11
	v_and_b32_e32 v11, 0xffff0000, v11
	v_mul_f32_e32 v16, 0xbfb8aa3b, v12
	v_mul_f32_e32 v17, 0xbfb8aa3b, v13
	v_mul_f32_e32 v18, 0xbfb8aa3b, v8
	v_mul_f32_e32 v19, 0xbfb8aa3b, v9
	v_mul_f32_e32 v20, 0xbfb8aa3b, v14
	v_mul_f32_e32 v21, 0xbfb8aa3b, v15
	v_mul_f32_e32 v22, 0xbfb8aa3b, v10
	v_mul_f32_e32 v23, 0xbfb8aa3b, v11
	v_exp_f32_e32 v16, v16
	v_exp_f32_e32 v17, v17
	v_exp_f32_e32 v18, v18
	v_exp_f32_e32 v19, v19
	v_exp_f32_e32 v20, v20
	v_exp_f32_e32 v21, v21
	v_exp_f32_e32 v22, v22
	v_exp_f32_e32 v23, v23
	v_add_f32_e32 v16, 1.0, v16
	v_add_f32_e32 v17, 1.0, v17
	v_add_f32_e32 v18, 1.0, v18
	v_add_f32_e32 v19, 1.0, v19
	v_add_f32_e32 v20, 1.0, v20
	v_add_f32_e32 v21, 1.0, v21
	v_add_f32_e32 v22, 1.0, v22
	v_add_f32_e32 v23, 1.0, v23
	v_rcp_f32_e32 v16, v16
	v_rcp_f32_e32 v17, v17
	v_rcp_f32_e32 v18, v18
	v_rcp_f32_e32 v19, v19
	v_rcp_f32_e32 v20, v20
	v_rcp_f32_e32 v21, v21
	v_rcp_f32_e32 v22, v22
	v_rcp_f32_e32 v23, v23
	v_pk_mul_f32 v[12:13], v[16:17], v[12:13]
	v_pk_mul_f32 v[8:9], v[18:19], v[8:9]
	v_pk_mul_f32 v[14:15], v[20:21], v[14:15]
	v_pk_mul_f32 v[10:11], v[22:23], v[10:11]
	v_pk_mul_f32 v[4:5], v[4:5], v[12:13]
	v_pk_mul_f32 v[6:7], v[6:7], v[8:9]
	v_pk_mul_f32 v[8:9], v[0:1], v[14:15]
	v_pk_mul_f32 v[10:11], v[2:3], v[10:11]
	v_cvt_pk_bf16_f32 v0, v4, v5
	v_cvt_pk_bf16_f32 v1, v6, v7
	v_cvt_pk_bf16_f32 v2, v8, v9
	v_cvt_pk_bf16_f32 v3, v10, v11
	global_store_dwordx4 v[72:73], v[0:3], off offset:256
	s_cbranch_vccnz .LBB0_1417
	s_andn2_b64 vcc, exec, s[4:5]
	s_cbranch_vccnz .LBB0_1416
	s_barrier
	s_branch .LBB0_1416
